# also drop accumulator zeroing in the single-unit GEMM phases P2/P8/P10 (first MFMAs take SrcC=0)
# baseline (speedup 1.0000x reference)
; #define PG8_STAGE(bufoff, gbase, voff) do { _Pragma("unroll") for (int _i = 0; _i < 2; ++_i) \
;         __builtin_amdgcn_global_load_lds((const unsigned*)((const char*)(gbase) + (voff)[_i]), (LAS unsigned*)(lds + (bufoff) + ldsw + _i * 8192), 16, 0, 0); } while (0)
; #define PG8_LDA(dst, b, h) do { _Pragma("unroll") for (int m = 0; m < 4; ++m) _Pragma("unroll") for (int k = 0; k < 2; ++k) dst[m][k] = *(const LAS bf16x8*)(lds + PG8_SA(b, h) + aoff + m * 2048 + k * 1024); } while (0)
; #define PG8_LDB(dst, b, h) do { _Pragma("unroll") for (int n = 0; n < 2; ++n) _Pragma("unroll") for (int k = 0; k < 2; ++k) dst[n][k] = *(const LAS bf16x8*)(lds + PG8_SB(b, h) + boff + n * 2048 + k * 1024); } while (0)
; #define PG8_MMA(ai, bj, At, Bt) do { __builtin_amdgcn_s_setprio(1); _Pragma("unroll") for (int m = 0; m < 4; ++m) _Pragma("unroll") for (int n = 0; n < 2; ++n) _Pragma("unroll") for (int k = 0; k < 2; ++k) \
;         acc[ai][bj][m][n] = __builtin_amdgcn_mfma_f32_16x16x32_bf16(Bt[n][k], At[m][k], acc[ai][bj][m][n], 0, 0, 0); __builtin_amdgcn_s_setprio(0); } while (0)
; #define PG8_WAIT_V(n) asm volatile("s_waitcnt vmcnt(" #n ")" ::: "memory")
; #define PG8_WAIT_L(n) asm volatile("s_waitcnt lgkmcnt(" #n ")" ::: "memory")
; #define PG8_BAR __builtin_amdgcn_s_barrier()
; #define PG8_SCHED __builtin_amdgcn_sched_barrier(0)
; template <class Epi>
; __device__ __forceinline__ void gemm_phase(LAS unsigned char* lds, const Gemm g, const Sched& S, const Epi& E) {
;     ...
;     for (int a = 0; a < 2; ++a)
; #pragma unroll
;         for (int b = 0; b < 2; ++b)
; #pragma unroll
;             for (int m = 0; m < 4; ++m)
; #pragma unroll
;                 for (int n = 0; n < 2; ++n) acc[a][b][m][n] = (f32x4){0.f, 0.f, 0.f, 0.f};
;     ...
;             PG8_LDB(B0, 0, 0); PG8_LDB(B1, 0, 1); PG8_SCHED; PG8_LDA(At, 0, 0); PG8_STAGE(PG8_SA(1, 1), a1 + hstepA, voffA);
;             PG8_WAIT_V(8); PG8_WAIT_L(0); PG8_BAR; PG8_MMA(0, 0, At, B0); PG8_MMA(0, 1, At, B1); PG8_BAR; PG8_SCHED;
;             PG8_LDA(At, 0, 1); PG8_STAGE(PG8_SB(0, 0), b2, voffB); PG8_STAGE(PG8_SB(0, 1), b2 + hstepB, voffB); PG8_STAGE(PG8_SA(0, 0), a2, voffA);
;             PG8_WAIT_V(8); PG8_WAIT_L(0); PG8_BAR; PG8_MMA(1, 0, At, B0); PG8_MMA(1, 1, At, B1); PG8_BAR; PG8_SCHED;
.LBB0_677:
	s_add_u32 s38, s38, 0xb0080
	s_addc_u32 s39, s39, 0
	s_add_u32 s85, s40, 0x100
	s_addc_u32 s86, s41, 0
	s_mov_b32 s87, -2
	s_waitcnt lgkmcnt(0)
	s_waitcnt lgkmcnt(0)
.LBB0_678:
	ds_read_b128 v[118:121], v214
	ds_read_b128 v[126:129], v214 offset:1024
	ds_read_b128 v[138:141], v214 offset:2048
	ds_read_b128 v[142:145], v214 offset:3072
	ds_read_b128 v[146:149], v215
	ds_read_b128 v[150:153], v215 offset:1024
	ds_read_b128 v[154:157], v215 offset:2048
	ds_read_b128 v[158:161], v215 offset:3072
	s_add_u32 s40, s38, 0xfff50080
	s_addc_u32 s41, s39, -1
	s_cmp_eq_u32 s87, 40
	s_cselect_b32 s53, s9, s41
	s_cselect_b32 s52, s8, s40
	s_cselect_b32 s41, s35, s86
	s_cselect_b32 s40, s34, s85
	v_lshl_add_u64 v[222:223], s[38:39], 0, v[196:197]
	s_add_i32 m0, s24, 0xc000
	ds_read_b128 v[162:165], v216
	ds_read_b128 v[166:169], v216 offset:1024
	ds_read_b128 v[170:173], v216 offset:2048
	ds_read_b128 v[174:177], v216 offset:3072
	ds_read_b128 v[178:181], v216 offset:4096
	ds_read_b128 v[182:185], v216 offset:5120
	ds_read_b128 v[206:209], v216 offset:6144
	ds_read_b128 v[218:221], v216 offset:7168
	global_load_lds_dwordx4 v[222:223], off
	v_lshl_add_u64 v[222:223], s[38:39], 0, v[200:201]
	s_add_i32 m0, s24, 0xe000
	s_nop 0
	global_load_lds_dwordx4 v[222:223], off
	s_waitcnt vmcnt(8)
	s_waitcnt lgkmcnt(0)
	s_cmp_eq_u32 s87, -2
	s_cbranch_scc1 .Lcz_p2_0
	s_barrier
	s_setprio 1
	s_waitcnt lgkmcnt(0)
	v_mfma_f32_16x16x32_bf16 v[134:137], v[118:121], v[162:165], v[134:137]
	v_mfma_f32_16x16x32_bf16 v[130:133], v[138:141], v[162:165], v[130:133]
	v_mfma_f32_16x16x32_bf16 v[110:113], v[118:121], v[170:173], v[110:113]
	v_mfma_f32_16x16x32_bf16 v[106:109], v[138:141], v[170:173], v[106:109]
	v_mfma_f32_16x16x32_bf16 v[94:97], v[118:121], v[178:181], v[94:97]
	v_mfma_f32_16x16x32_bf16 v[90:93], v[138:141], v[178:181], v[90:93]
	v_mfma_f32_16x16x32_bf16 v[78:81], v[118:121], v[206:209], v[78:81]
	v_mfma_f32_16x16x32_bf16 v[74:77], v[138:141], v[206:209], v[74:77]
	v_mfma_f32_16x16x32_bf16 v[134:137], v[126:129], v[166:169], v[134:137]
	v_mfma_f32_16x16x32_bf16 v[130:133], v[142:145], v[166:169], v[130:133]
	v_mfma_f32_16x16x32_bf16 v[110:113], v[126:129], v[174:177], v[110:113]
	v_mfma_f32_16x16x32_bf16 v[106:109], v[142:145], v[174:177], v[106:109]
	v_mfma_f32_16x16x32_bf16 v[94:97], v[126:129], v[182:185], v[94:97]
	v_mfma_f32_16x16x32_bf16 v[90:93], v[142:145], v[182:185], v[90:93]
	v_mfma_f32_16x16x32_bf16 v[78:81], v[126:129], v[218:221], v[78:81]
	v_mfma_f32_16x16x32_bf16 v[74:77], v[142:145], v[218:221], v[74:77]
	s_setprio 0
	s_setprio 1
	v_mfma_f32_16x16x32_bf16 v[122:125], v[146:149], v[162:165], v[122:125]
	v_mfma_f32_16x16x32_bf16 v[114:117], v[154:157], v[162:165], v[114:117]
	v_mfma_f32_16x16x32_bf16 v[102:105], v[146:149], v[170:173], v[102:105]
	v_mfma_f32_16x16x32_bf16 v[98:101], v[154:157], v[170:173], v[98:101]
	v_mfma_f32_16x16x32_bf16 v[86:89], v[146:149], v[178:181], v[86:89]
	v_mfma_f32_16x16x32_bf16 v[82:85], v[154:157], v[178:181], v[82:85]
	v_mfma_f32_16x16x32_bf16 v[70:73], v[146:149], v[206:209], v[70:73]
	v_mfma_f32_16x16x32_bf16 v[66:69], v[154:157], v[206:209], v[66:69]
	v_mfma_f32_16x16x32_bf16 v[122:125], v[150:153], v[166:169], v[122:125]
	v_mfma_f32_16x16x32_bf16 v[114:117], v[158:161], v[166:169], v[114:117]
	v_mfma_f32_16x16x32_bf16 v[102:105], v[150:153], v[174:177], v[102:105]
	v_mfma_f32_16x16x32_bf16 v[98:101], v[158:161], v[174:177], v[98:101]
	v_mfma_f32_16x16x32_bf16 v[86:89], v[150:153], v[182:185], v[86:89]
	v_mfma_f32_16x16x32_bf16 v[82:85], v[158:161], v[182:185], v[82:85]
	v_mfma_f32_16x16x32_bf16 v[70:73], v[150:153], v[218:221], v[70:73]
	v_mfma_f32_16x16x32_bf16 v[66:69], v[158:161], v[218:221], v[66:69]
.Lcz_p2_0_j:
	s_setprio 0
	s_barrier
	s_add_i32 s88, s77, s3
	v_lshl_add_u64 v[222:223], s[40:41], 0, v[188:189]
	s_mov_b32 m0, s88
	ds_read_b128 v[162:165], v216 offset:16384
	ds_read_b128 v[166:169], v216 offset:17408
	ds_read_b128 v[170:173], v216 offset:18432
	ds_read_b128 v[174:177], v216 offset:19456
	ds_read_b128 v[178:181], v216 offset:20480
	ds_read_b128 v[182:185], v216 offset:21504
	ds_read_b128 v[206:209], v216 offset:22528
	ds_read_b128 v[218:221], v216 offset:23552
	global_load_lds_dwordx4 v[222:223], off
	s_add_i32 m0, s88, 0x2000
	s_add_u32 s88, s40, 0xb0000
	v_lshl_add_u64 v[224:225], s[40:41], 0, v[192:193]
	s_addc_u32 s89, s41, 0
	s_add_i32 s90, s78, s3
	global_load_lds_dwordx4 v[224:225], off
	v_lshl_add_u64 v[226:227], s[88:89], 0, v[188:189]
	s_mov_b32 m0, s90
	v_lshl_add_u64 v[228:229], s[52:53], 0, v[190:191]
	global_load_lds_dwordx4 v[226:227], off
	v_lshl_add_u64 v[226:227], s[88:89], 0, v[192:193]
	s_add_i32 m0, s90, 0x2000
	s_nop 0
	global_load_lds_dwordx4 v[226:227], off
	v_lshl_add_u64 v[226:227], s[52:53], 0, v[186:187]
	s_mov_b32 m0, s24
	s_nop 0
	global_load_lds_dwordx4 v[226:227], off
	s_mov_b32 m0, s25
	s_nop 0
	global_load_lds_dwordx4 v[228:229], off
	s_waitcnt vmcnt(8)
	s_waitcnt lgkmcnt(0)
	s_cmp_eq_u32 s87, -2
	s_cbranch_scc1 .Lcz_p2_1
	s_barrier
; #define PG8_STAGE(bufoff, gbase, voff) do { _Pragma("unroll") for (int _i = 0; _i < 2; ++_i) \
;         __builtin_amdgcn_global_load_lds((const unsigned*)((const char*)(gbase) + (voff)[_i]), (LAS unsigned*)(lds + (bufoff) + ldsw + _i * 8192), 16, 0, 0); } while (0)
; #define PG8_LDA(dst, b, h) do { _Pragma("unroll") for (int m = 0; m < 4; ++m) _Pragma("unroll") for (int k = 0; k < 2; ++k) dst[m][k] = *(const LAS bf16x8*)(lds + PG8_SA(b, h) + aoff + m * 2048 + k * 1024); } while (0)
; #define PG8_LDB(dst, b, h) do { _Pragma("unroll") for (int n = 0; n < 2; ++n) _Pragma("unroll") for (int k = 0; k < 2; ++k) dst[n][k] = *(const LAS bf16x8*)(lds + PG8_SB(b, h) + boff + n * 2048 + k * 1024); } while (0)
; #define PG8_MMA(ai, bj, At, Bt) do { __builtin_amdgcn_s_setprio(1); _Pragma("unroll") for (int m = 0; m < 4; ++m) _Pragma("unroll") for (int n = 0; n < 2; ++n) _Pragma("unroll") for (int k = 0; k < 2; ++k) \
;         acc[ai][bj][m][n] = __builtin_amdgcn_mfma_f32_16x16x32_bf16(Bt[n][k], At[m][k], acc[ai][bj][m][n], 0, 0, 0); __builtin_amdgcn_s_setprio(0); } while (0)
; #define PG8_WAIT_V(n) asm volatile("s_waitcnt vmcnt(" #n ")" ::: "memory")
; #define PG8_WAIT_L(n) asm volatile("s_waitcnt lgkmcnt(" #n ")" ::: "memory")
; #define PG8_BAR __builtin_amdgcn_s_barrier()
; #define PG8_SCHED __builtin_amdgcn_sched_barrier(0)
; template <class Epi>
; __device__ __forceinline__ void gemm_phase(LAS unsigned char* lds, const Gemm g, const Sched& S, const Epi& E) {
;     ...
;             PG8_WAIT_V(8); PG8_WAIT_L(0); PG8_BAR; PG8_MMA(1, 0, At, B0); PG8_MMA(1, 1, At, B1); PG8_BAR; PG8_SCHED;
;             PG8_LDB(B0, 1, 0); PG8_LDB(B1, 1, 1); PG8_SCHED; PG8_LDA(At, 1, 0); PG8_STAGE(PG8_SA(0, 1), a2 + hstepA, voffA);
;             PG8_WAIT_V(8); PG8_WAIT_L(0); PG8_BAR; PG8_MMA(0, 0, At, B0); PG8_MMA(0, 1, At, B1); PG8_BAR; PG8_SCHED;
	s_setprio 1
	s_waitcnt lgkmcnt(0)
	v_mfma_f32_16x16x32_bf16 v[62:65], v[118:121], v[162:165], v[62:65]
	v_mfma_f32_16x16x32_bf16 v[58:61], v[138:141], v[162:165], v[58:61]
	v_mfma_f32_16x16x32_bf16 v[46:49], v[118:121], v[170:173], v[46:49]
	v_mfma_f32_16x16x32_bf16 v[42:45], v[138:141], v[170:173], v[42:45]
	v_mfma_f32_16x16x32_bf16 v[30:33], v[118:121], v[178:181], v[30:33]
	v_mfma_f32_16x16x32_bf16 v[26:29], v[138:141], v[178:181], v[26:29]
	v_mfma_f32_16x16x32_bf16 v[14:17], v[118:121], v[206:209], v[14:17]
	v_mfma_f32_16x16x32_bf16 v[10:13], v[138:141], v[206:209], v[10:13]
	v_mfma_f32_16x16x32_bf16 v[62:65], v[126:129], v[166:169], v[62:65]
	v_mfma_f32_16x16x32_bf16 v[58:61], v[142:145], v[166:169], v[58:61]
	v_mfma_f32_16x16x32_bf16 v[46:49], v[126:129], v[174:177], v[46:49]
	v_mfma_f32_16x16x32_bf16 v[42:45], v[142:145], v[174:177], v[42:45]
	v_mfma_f32_16x16x32_bf16 v[30:33], v[126:129], v[182:185], v[30:33]
	v_mfma_f32_16x16x32_bf16 v[26:29], v[142:145], v[182:185], v[26:29]
	v_mfma_f32_16x16x32_bf16 v[14:17], v[126:129], v[218:221], v[14:17]
	v_mfma_f32_16x16x32_bf16 v[10:13], v[142:145], v[218:221], v[10:13]
	s_setprio 0
	s_setprio 1
	v_mfma_f32_16x16x32_bf16 v[54:57], v[146:149], v[162:165], v[54:57]
	v_mfma_f32_16x16x32_bf16 v[50:53], v[154:157], v[162:165], v[50:53]
	v_mfma_f32_16x16x32_bf16 v[38:41], v[146:149], v[170:173], v[38:41]
	v_mfma_f32_16x16x32_bf16 v[34:37], v[154:157], v[170:173], v[34:37]
	v_mfma_f32_16x16x32_bf16 v[22:25], v[146:149], v[178:181], v[22:25]
	v_mfma_f32_16x16x32_bf16 v[18:21], v[154:157], v[178:181], v[18:21]
	v_mfma_f32_16x16x32_bf16 v[6:9], v[146:149], v[206:209], v[6:9]
	v_mfma_f32_16x16x32_bf16 v[2:5], v[154:157], v[206:209], v[2:5]
	v_mfma_f32_16x16x32_bf16 v[54:57], v[150:153], v[166:169], v[54:57]
	v_mfma_f32_16x16x32_bf16 v[50:53], v[158:161], v[166:169], v[50:53]
	v_mfma_f32_16x16x32_bf16 v[38:41], v[150:153], v[174:177], v[38:41]
	v_mfma_f32_16x16x32_bf16 v[34:37], v[158:161], v[174:177], v[34:37]
	v_mfma_f32_16x16x32_bf16 v[22:25], v[150:153], v[182:185], v[22:25]
	v_mfma_f32_16x16x32_bf16 v[18:21], v[158:161], v[182:185], v[18:21]
	v_mfma_f32_16x16x32_bf16 v[6:9], v[150:153], v[218:221], v[6:9]
	v_mfma_f32_16x16x32_bf16 v[2:5], v[158:161], v[218:221], v[2:5]
.Lcz_p2_1_j:
	s_setprio 0
	s_barrier
	s_add_i32 s88, 0, 0x18000
	s_add_i32 s89, 0, 0x1c000
	v_add_u32_e32 v142, s88, v213
	v_add_u32_e32 v158, s89, v213
	ds_read_b128 v[118:121], v142
	ds_read_b128 v[126:129], v142 offset:1024
	ds_read_b128 v[138:141], v142 offset:2048
	ds_read_b128 v[142:145], v142 offset:3072
	ds_read_b128 v[146:149], v158
	ds_read_b128 v[150:153], v158 offset:1024
	ds_read_b128 v[154:157], v158 offset:2048
	ds_read_b128 v[158:161], v158 offset:3072
	s_add_u32 s52, s52, 0xb0000
	s_addc_u32 s53, s53, 0
	s_mov_b32 m0, s33
	v_lshl_add_u64 v[230:231], s[52:53], 0, v[186:187]
	ds_read_b128 v[162:165], v216 offset:32768
	ds_read_b128 v[166:169], v216 offset:33792
	ds_read_b128 v[170:173], v216 offset:34816
	ds_read_b128 v[174:177], v216 offset:35840
	ds_read_b128 v[178:181], v216 offset:36864
	ds_read_b128 v[182:185], v216 offset:37888
	ds_read_b128 v[206:209], v216 offset:38912
	ds_read_b128 v[218:221], v216 offset:39936
	global_load_lds_dwordx4 v[230:231], off
	v_lshl_add_u64 v[230:231], s[52:53], 0, v[190:191]
	s_mov_b32 m0, s54
	s_nop 0
	global_load_lds_dwordx4 v[230:231], off
	s_waitcnt vmcnt(8)
	s_waitcnt lgkmcnt(0)
	s_barrier
	s_setprio 1
	s_waitcnt lgkmcnt(0)
	v_mfma_f32_16x16x32_bf16 v[134:137], v[118:121], v[162:165], v[134:137]
	v_mfma_f32_16x16x32_bf16 v[130:133], v[138:141], v[162:165], v[130:133]
	v_mfma_f32_16x16x32_bf16 v[110:113], v[118:121], v[170:173], v[110:113]
	v_mfma_f32_16x16x32_bf16 v[106:109], v[138:141], v[170:173], v[106:109]
	v_mfma_f32_16x16x32_bf16 v[94:97], v[118:121], v[178:181], v[94:97]
	v_mfma_f32_16x16x32_bf16 v[90:93], v[138:141], v[178:181], v[90:93]
	v_mfma_f32_16x16x32_bf16 v[78:81], v[118:121], v[206:209], v[78:81]
	v_mfma_f32_16x16x32_bf16 v[74:77], v[138:141], v[206:209], v[74:77]
	v_mfma_f32_16x16x32_bf16 v[134:137], v[126:129], v[166:169], v[134:137]
	v_mfma_f32_16x16x32_bf16 v[130:133], v[142:145], v[166:169], v[130:133]
	v_mfma_f32_16x16x32_bf16 v[110:113], v[126:129], v[174:177], v[110:113]
	v_mfma_f32_16x16x32_bf16 v[106:109], v[142:145], v[174:177], v[106:109]
	v_mfma_f32_16x16x32_bf16 v[94:97], v[126:129], v[182:185], v[94:97]
	v_mfma_f32_16x16x32_bf16 v[90:93], v[142:145], v[182:185], v[90:93]
	v_mfma_f32_16x16x32_bf16 v[78:81], v[126:129], v[218:221], v[78:81]
	v_mfma_f32_16x16x32_bf16 v[74:77], v[142:145], v[218:221], v[74:77]
	s_setprio 0
	s_setprio 1
	v_mfma_f32_16x16x32_bf16 v[122:125], v[146:149], v[162:165], v[122:125]
	v_mfma_f32_16x16x32_bf16 v[114:117], v[154:157], v[162:165], v[114:117]
	v_mfma_f32_16x16x32_bf16 v[102:105], v[146:149], v[170:173], v[102:105]
	v_mfma_f32_16x16x32_bf16 v[98:101], v[154:157], v[170:173], v[98:101]
	v_mfma_f32_16x16x32_bf16 v[86:89], v[146:149], v[178:181], v[86:89]
	v_mfma_f32_16x16x32_bf16 v[82:85], v[154:157], v[178:181], v[82:85]
	v_mfma_f32_16x16x32_bf16 v[70:73], v[146:149], v[206:209], v[70:73]
	v_mfma_f32_16x16x32_bf16 v[66:69], v[154:157], v[206:209], v[66:69]
	v_mfma_f32_16x16x32_bf16 v[122:125], v[150:153], v[166:169], v[122:125]
	v_mfma_f32_16x16x32_bf16 v[114:117], v[158:161], v[166:169], v[114:117]
	v_mfma_f32_16x16x32_bf16 v[102:105], v[150:153], v[174:177], v[102:105]
	v_mfma_f32_16x16x32_bf16 v[98:101], v[158:161], v[174:177], v[98:101]
	v_mfma_f32_16x16x32_bf16 v[86:89], v[150:153], v[182:185], v[86:89]
	v_mfma_f32_16x16x32_bf16 v[82:85], v[158:161], v[182:185], v[82:85]
	v_mfma_f32_16x16x32_bf16 v[70:73], v[150:153], v[218:221], v[70:73]
	v_mfma_f32_16x16x32_bf16 v[66:69], v[158:161], v[218:221], v[66:69]
	s_setprio 0
	s_barrier
; #define PG8_STAGE(bufoff, gbase, voff) do { _Pragma("unroll") for (int _i = 0; _i < 2; ++_i) \
;         __builtin_amdgcn_global_load_lds((const unsigned*)((const char*)(gbase) + (voff)[_i]), (LAS unsigned*)(lds + (bufoff) + ldsw + _i * 8192), 16, 0, 0); } while (0)
; #define PG8_LDA(dst, b, h) do { _Pragma("unroll") for (int m = 0; m < 4; ++m) _Pragma("unroll") for (int k = 0; k < 2; ++k) dst[m][k] = *(const LAS bf16x8*)(lds + PG8_SA(b, h) + aoff + m * 2048 + k * 1024); } while (0)
; #define PG8_MMA(ai, bj, At, Bt) do { __builtin_amdgcn_s_setprio(1); _Pragma("unroll") for (int m = 0; m < 4; ++m) _Pragma("unroll") for (int n = 0; n < 2; ++n) _Pragma("unroll") for (int k = 0; k < 2; ++k) \
;         acc[ai][bj][m][n] = __builtin_amdgcn_mfma_f32_16x16x32_bf16(Bt[n][k], At[m][k], acc[ai][bj][m][n], 0, 0, 0); __builtin_amdgcn_s_setprio(0); } while (0)
; #define PG8_WAIT_V(n) asm volatile("s_waitcnt vmcnt(" #n ")" ::: "memory")
; #define PG8_WAIT_L(n) asm volatile("s_waitcnt lgkmcnt(" #n ")" ::: "memory")
; #define PG8_BAR __builtin_amdgcn_s_barrier()
; #define PG8_SCHED __builtin_amdgcn_sched_barrier(0)
; template <class Epi>
; __device__ __forceinline__ void gemm_phase(LAS unsigned char* lds, const Gemm g, const Sched& S, const Epi& E) {
;     ...
;             PG8_LDA(At, 1, 1); PG8_STAGE(PG8_SB(1, 0), b3, voffB); PG8_STAGE(PG8_SB(1, 1), b3 + hstepB, voffB); PG8_STAGE(PG8_SA(1, 0), a3, voffA);
;             PG8_WAIT_V(8); PG8_WAIT_L(0); PG8_BAR; PG8_MMA(1, 0, At, B0); PG8_MMA(1, 1, At, B1); PG8_BAR; PG8_SCHED;
;         }
;         if (wr == 0) PG8_BAR;
	s_add_i32 s52, s88, s3
	v_lshl_add_u64 v[222:223], v[222:223], 0, s[28:29]
	s_mov_b32 m0, s52
	ds_read_b128 v[162:165], v216 offset:49152
	ds_read_b128 v[166:169], v216 offset:50176
	ds_read_b128 v[170:173], v216 offset:51200
	ds_read_b128 v[174:177], v216 offset:52224
	ds_read_b128 v[178:181], v216 offset:53248
	ds_read_b128 v[182:185], v216 offset:54272
	ds_read_b128 v[206:209], v216 offset:55296
	ds_read_b128 v[218:221], v216 offset:56320
	global_load_lds_dwordx4 v[222:223], off
	s_add_i32 m0, s52, 0x2000
	s_add_u32 s40, s40, 0xb0080
	v_lshl_add_u64 v[222:223], v[224:225], 0, s[28:29]
	s_addc_u32 s41, s41, 0
	s_add_i32 s52, s89, s3
	global_load_lds_dwordx4 v[222:223], off
	v_lshl_add_u64 v[222:223], s[40:41], 0, v[188:189]
	s_mov_b32 m0, s52
	s_nop 0
	global_load_lds_dwordx4 v[222:223], off
	v_lshl_add_u64 v[222:223], s[40:41], 0, v[192:193]
	s_add_i32 m0, s52, 0x2000
	s_nop 0
	global_load_lds_dwordx4 v[222:223], off
	v_lshl_add_u64 v[222:223], v[226:227], 0, s[28:29]
	s_mov_b32 m0, s72
	s_nop 0
	global_load_lds_dwordx4 v[222:223], off
	v_lshl_add_u64 v[222:223], v[228:229], 0, s[28:29]
	s_mov_b32 m0, s73
	s_nop 0
	global_load_lds_dwordx4 v[222:223], off
	s_waitcnt vmcnt(8)
	s_waitcnt lgkmcnt(0)
	s_barrier
	s_setprio 1
	s_waitcnt lgkmcnt(0)
	v_mfma_f32_16x16x32_bf16 v[62:65], v[118:121], v[162:165], v[62:65]
	v_mfma_f32_16x16x32_bf16 v[58:61], v[138:141], v[162:165], v[58:61]
	v_mfma_f32_16x16x32_bf16 v[46:49], v[118:121], v[170:173], v[46:49]
	v_mfma_f32_16x16x32_bf16 v[42:45], v[138:141], v[170:173], v[42:45]
	v_mfma_f32_16x16x32_bf16 v[30:33], v[118:121], v[178:181], v[30:33]
	v_mfma_f32_16x16x32_bf16 v[26:29], v[138:141], v[178:181], v[26:29]
	v_mfma_f32_16x16x32_bf16 v[14:17], v[118:121], v[206:209], v[14:17]
	v_mfma_f32_16x16x32_bf16 v[10:13], v[138:141], v[206:209], v[10:13]
	v_mfma_f32_16x16x32_bf16 v[62:65], v[126:129], v[166:169], v[62:65]
	v_mfma_f32_16x16x32_bf16 v[58:61], v[142:145], v[166:169], v[58:61]
	v_mfma_f32_16x16x32_bf16 v[46:49], v[126:129], v[174:177], v[46:49]
	v_mfma_f32_16x16x32_bf16 v[42:45], v[142:145], v[174:177], v[42:45]
	v_mfma_f32_16x16x32_bf16 v[30:33], v[126:129], v[182:185], v[30:33]
	v_mfma_f32_16x16x32_bf16 v[26:29], v[142:145], v[182:185], v[26:29]
	v_mfma_f32_16x16x32_bf16 v[14:17], v[126:129], v[218:221], v[14:17]
	v_mfma_f32_16x16x32_bf16 v[10:13], v[142:145], v[218:221], v[10:13]
	s_setprio 0
	s_setprio 1
	v_mfma_f32_16x16x32_bf16 v[54:57], v[146:149], v[162:165], v[54:57]
	v_mfma_f32_16x16x32_bf16 v[50:53], v[154:157], v[162:165], v[50:53]
	v_mfma_f32_16x16x32_bf16 v[38:41], v[146:149], v[170:173], v[38:41]
	v_mfma_f32_16x16x32_bf16 v[34:37], v[154:157], v[170:173], v[34:37]
	v_mfma_f32_16x16x32_bf16 v[22:25], v[146:149], v[178:181], v[22:25]
	v_mfma_f32_16x16x32_bf16 v[18:21], v[154:157], v[178:181], v[18:21]
	v_mfma_f32_16x16x32_bf16 v[6:9], v[146:149], v[206:209], v[6:9]
	v_mfma_f32_16x16x32_bf16 v[2:5], v[154:157], v[206:209], v[2:5]
	v_mfma_f32_16x16x32_bf16 v[54:57], v[150:153], v[166:169], v[54:57]
	v_mfma_f32_16x16x32_bf16 v[50:53], v[158:161], v[166:169], v[50:53]
	v_mfma_f32_16x16x32_bf16 v[38:41], v[150:153], v[174:177], v[38:41]
	v_mfma_f32_16x16x32_bf16 v[34:37], v[158:161], v[174:177], v[34:37]
	v_mfma_f32_16x16x32_bf16 v[22:25], v[150:153], v[182:185], v[22:25]
	v_mfma_f32_16x16x32_bf16 v[18:21], v[158:161], v[182:185], v[18:21]
	v_mfma_f32_16x16x32_bf16 v[6:9], v[150:153], v[218:221], v[6:9]
	v_mfma_f32_16x16x32_bf16 v[2:5], v[158:161], v[218:221], v[2:5]
	s_setprio 0
	s_barrier
	s_add_i32 s87, s87, 2
	s_add_u32 s38, s38, 0x100
	s_addc_u32 s39, s39, 0
	s_add_u32 s85, s85, 0x100
	s_addc_u32 s86, s86, 0
	s_cmp_gt_u32 s87, 41
	s_cbranch_scc0 .LBB0_678
	s_and_b64 vcc, exec, s[30:31]
	s_cbranch_vccz .LBB0_681
	s_barrier

; #define PG8_STAGE(bufoff, gbase, voff) do { _Pragma("unroll") for (int _i = 0; _i < 2; ++_i) \
;         __builtin_amdgcn_global_load_lds((const unsigned*)((const char*)(gbase) + (voff)[_i]), (LAS unsigned*)(lds + (bufoff) + ldsw + _i * 8192), 16, 0, 0); } while (0)
; #define PG8_LDA(dst, b, h) do { _Pragma("unroll") for (int m = 0; m < 4; ++m) _Pragma("unroll") for (int k = 0; k < 2; ++k) dst[m][k] = *(const LAS bf16x8*)(lds + PG8_SA(b, h) + aoff + m * 2048 + k * 1024); } while (0)
; #define PG8_MMA(ai, bj, At, Bt) do { __builtin_amdgcn_s_setprio(1); _Pragma("unroll") for (int m = 0; m < 4; ++m) _Pragma("unroll") for (int n = 0; n < 2; ++n) _Pragma("unroll") for (int k = 0; k < 2; ++k) \
;         acc[ai][bj][m][n] = __builtin_amdgcn_mfma_f32_16x16x32_bf16(Bt[n][k], At[m][k], acc[ai][bj][m][n], 0, 0, 0); __builtin_amdgcn_s_setprio(0); } while (0)
; #define PG8_WAIT_V(n) asm volatile("s_waitcnt vmcnt(" #n ")" ::: "memory")
; #define PG8_WAIT_L(n) asm volatile("s_waitcnt lgkmcnt(" #n ")" ::: "memory")
; #define PG8_BAR __builtin_amdgcn_s_barrier()
; #define PG8_SCHED __builtin_amdgcn_sched_barrier(0)
; template <class Epi>
; __device__ __forceinline__ void gemm_phase(LAS unsigned char* lds, const Gemm g, const Sched& S, const Epi& E) {
;     ...
;             PG8_WAIT_V(8); PG8_WAIT_L(0); PG8_BAR; PG8_MMA(0, 0, At, B0); PG8_MMA(0, 1, At, B1); PG8_BAR; PG8_SCHED;
;             PG8_LDA(At, 0, 1); PG8_STAGE(PG8_SB(0, 0), b2, voffB); PG8_STAGE(PG8_SB(0, 1), b2 + hstepB, voffB); PG8_STAGE(PG8_SA(0, 0), a2, voffA);
;             PG8_WAIT_V(8); PG8_WAIT_L(0); PG8_BAR; PG8_MMA(1, 0, At, B0); PG8_MMA(1, 1, At, B1); PG8_BAR; PG8_SCHED;
.Lcz_p2_0:
	s_barrier
	s_setprio 1
	s_waitcnt lgkmcnt(0)
	v_mfma_f32_16x16x32_bf16 v[134:137], v[118:121], v[162:165], 0
	v_mfma_f32_16x16x32_bf16 v[130:133], v[138:141], v[162:165], 0
	v_mfma_f32_16x16x32_bf16 v[110:113], v[118:121], v[170:173], 0
	v_mfma_f32_16x16x32_bf16 v[106:109], v[138:141], v[170:173], 0
	v_mfma_f32_16x16x32_bf16 v[94:97], v[118:121], v[178:181], 0
	v_mfma_f32_16x16x32_bf16 v[90:93], v[138:141], v[178:181], 0
	v_mfma_f32_16x16x32_bf16 v[78:81], v[118:121], v[206:209], 0
	v_mfma_f32_16x16x32_bf16 v[74:77], v[138:141], v[206:209], 0
	v_mfma_f32_16x16x32_bf16 v[134:137], v[126:129], v[166:169], v[134:137]
	v_mfma_f32_16x16x32_bf16 v[130:133], v[142:145], v[166:169], v[130:133]
	v_mfma_f32_16x16x32_bf16 v[110:113], v[126:129], v[174:177], v[110:113]
	v_mfma_f32_16x16x32_bf16 v[106:109], v[142:145], v[174:177], v[106:109]
	v_mfma_f32_16x16x32_bf16 v[94:97], v[126:129], v[182:185], v[94:97]
	v_mfma_f32_16x16x32_bf16 v[90:93], v[142:145], v[182:185], v[90:93]
	v_mfma_f32_16x16x32_bf16 v[78:81], v[126:129], v[218:221], v[78:81]
	v_mfma_f32_16x16x32_bf16 v[74:77], v[142:145], v[218:221], v[74:77]
	s_setprio 0
	s_setprio 1
	v_mfma_f32_16x16x32_bf16 v[122:125], v[146:149], v[162:165], 0
	v_mfma_f32_16x16x32_bf16 v[114:117], v[154:157], v[162:165], 0
	v_mfma_f32_16x16x32_bf16 v[102:105], v[146:149], v[170:173], 0
	v_mfma_f32_16x16x32_bf16 v[98:101], v[154:157], v[170:173], 0
	v_mfma_f32_16x16x32_bf16 v[86:89], v[146:149], v[178:181], 0
	v_mfma_f32_16x16x32_bf16 v[82:85], v[154:157], v[178:181], 0
	v_mfma_f32_16x16x32_bf16 v[70:73], v[146:149], v[206:209], 0
	v_mfma_f32_16x16x32_bf16 v[66:69], v[154:157], v[206:209], 0
	v_mfma_f32_16x16x32_bf16 v[122:125], v[150:153], v[166:169], v[122:125]
	v_mfma_f32_16x16x32_bf16 v[114:117], v[158:161], v[166:169], v[114:117]
	v_mfma_f32_16x16x32_bf16 v[102:105], v[150:153], v[174:177], v[102:105]
	v_mfma_f32_16x16x32_bf16 v[98:101], v[158:161], v[174:177], v[98:101]
	v_mfma_f32_16x16x32_bf16 v[86:89], v[150:153], v[182:185], v[86:89]
	v_mfma_f32_16x16x32_bf16 v[82:85], v[158:161], v[182:185], v[82:85]
	v_mfma_f32_16x16x32_bf16 v[70:73], v[150:153], v[218:221], v[70:73]
	v_mfma_f32_16x16x32_bf16 v[66:69], v[158:161], v[218:221], v[66:69]
	s_branch .Lcz_p2_0_j
.Lcz_p2_1:
	s_barrier
	s_setprio 1
	s_waitcnt lgkmcnt(0)
	v_mfma_f32_16x16x32_bf16 v[62:65], v[118:121], v[162:165], 0
	v_mfma_f32_16x16x32_bf16 v[58:61], v[138:141], v[162:165], 0
	v_mfma_f32_16x16x32_bf16 v[46:49], v[118:121], v[170:173], 0
	v_mfma_f32_16x16x32_bf16 v[42:45], v[138:141], v[170:173], 0
	v_mfma_f32_16x16x32_bf16 v[30:33], v[118:121], v[178:181], 0
	v_mfma_f32_16x16x32_bf16 v[26:29], v[138:141], v[178:181], 0
	v_mfma_f32_16x16x32_bf16 v[14:17], v[118:121], v[206:209], 0
	v_mfma_f32_16x16x32_bf16 v[10:13], v[138:141], v[206:209], 0
	v_mfma_f32_16x16x32_bf16 v[62:65], v[126:129], v[166:169], v[62:65]
	v_mfma_f32_16x16x32_bf16 v[58:61], v[142:145], v[166:169], v[58:61]
	v_mfma_f32_16x16x32_bf16 v[46:49], v[126:129], v[174:177], v[46:49]
	v_mfma_f32_16x16x32_bf16 v[42:45], v[142:145], v[174:177], v[42:45]
	v_mfma_f32_16x16x32_bf16 v[30:33], v[126:129], v[182:185], v[30:33]
	v_mfma_f32_16x16x32_bf16 v[26:29], v[142:145], v[182:185], v[26:29]
	v_mfma_f32_16x16x32_bf16 v[14:17], v[126:129], v[218:221], v[14:17]
	v_mfma_f32_16x16x32_bf16 v[10:13], v[142:145], v[218:221], v[10:13]
	s_setprio 0
	s_setprio 1
	v_mfma_f32_16x16x32_bf16 v[54:57], v[146:149], v[162:165], 0
	v_mfma_f32_16x16x32_bf16 v[50:53], v[154:157], v[162:165], 0
	v_mfma_f32_16x16x32_bf16 v[38:41], v[146:149], v[170:173], 0
	v_mfma_f32_16x16x32_bf16 v[34:37], v[154:157], v[170:173], 0
	v_mfma_f32_16x16x32_bf16 v[22:25], v[146:149], v[178:181], 0
	v_mfma_f32_16x16x32_bf16 v[18:21], v[154:157], v[178:181], 0
	v_mfma_f32_16x16x32_bf16 v[6:9], v[146:149], v[206:209], 0
	v_mfma_f32_16x16x32_bf16 v[2:5], v[154:157], v[206:209], 0
	v_mfma_f32_16x16x32_bf16 v[54:57], v[150:153], v[166:169], v[54:57]
	v_mfma_f32_16x16x32_bf16 v[50:53], v[158:161], v[166:169], v[50:53]
	v_mfma_f32_16x16x32_bf16 v[38:41], v[150:153], v[174:177], v[38:41]
	v_mfma_f32_16x16x32_bf16 v[34:37], v[158:161], v[174:177], v[34:37]
	v_mfma_f32_16x16x32_bf16 v[22:25], v[150:153], v[182:185], v[22:25]
	v_mfma_f32_16x16x32_bf16 v[18:21], v[158:161], v[182:185], v[18:21]
	v_mfma_f32_16x16x32_bf16 v[6:9], v[150:153], v[218:221], v[6:9]
	v_mfma_f32_16x16x32_bf16 v[2:5], v[158:161], v[218:221], v[2:5]
	s_branch .Lcz_p2_1_j

; #define PG8_STAGE(bufoff, gbase, voff) do { _Pragma("unroll") for (int _i = 0; _i < 2; ++_i) \
;         __builtin_amdgcn_global_load_lds((const unsigned*)((const char*)(gbase) + (voff)[_i]), (LAS unsigned*)(lds + (bufoff) + ldsw + _i * 8192), 16, 0, 0); } while (0)
; #define PG8_LDA(dst, b, h) do { _Pragma("unroll") for (int m = 0; m < 4; ++m) _Pragma("unroll") for (int k = 0; k < 2; ++k) dst[m][k] = *(const LAS bf16x8*)(lds + PG8_SA(b, h) + aoff + m * 2048 + k * 1024); } while (0)
; #define PG8_LDB(dst, b, h) do { _Pragma("unroll") for (int n = 0; n < 2; ++n) _Pragma("unroll") for (int k = 0; k < 2; ++k) dst[n][k] = *(const LAS bf16x8*)(lds + PG8_SB(b, h) + boff + n * 2048 + k * 1024); } while (0)
; #define PG8_MMA(ai, bj, At, Bt) do { __builtin_amdgcn_s_setprio(1); _Pragma("unroll") for (int m = 0; m < 4; ++m) _Pragma("unroll") for (int n = 0; n < 2; ++n) _Pragma("unroll") for (int k = 0; k < 2; ++k) \
;         acc[ai][bj][m][n] = __builtin_amdgcn_mfma_f32_16x16x32_bf16(Bt[n][k], At[m][k], acc[ai][bj][m][n], 0, 0, 0); __builtin_amdgcn_s_setprio(0); } while (0)
; #define PG8_WAIT_V(n) asm volatile("s_waitcnt vmcnt(" #n ")" ::: "memory")
; #define PG8_WAIT_L(n) asm volatile("s_waitcnt lgkmcnt(" #n ")" ::: "memory")
; #define PG8_BAR __builtin_amdgcn_s_barrier()
; #define PG8_SCHED __builtin_amdgcn_sched_barrier(0)
; template <class Epi>
; __device__ __forceinline__ void gemm_phase(LAS unsigned char* lds, const Gemm g, const Sched& S, const Epi& E) {
;     ...
;         const char* nA = has_next ? (const char*)g.A + (size_t)nxt.pm * tstepA + (size_t)nxt.part * g.koff * 2 : cA; const char* nB = has_next ? (const char*)g.Bt + (size_t)nxt.pn * tstepB + (size_t)nxt.part * g.koff * 2 : cB;
;     ...
;             PG8_LDB(B0, 0, 0); PG8_LDB(B1, 0, 1); PG8_SCHED; PG8_LDA(At, 0, 0); PG8_STAGE(PG8_SA(1, 1), a1 + hstepA, voffA);
;             PG8_WAIT_V(8); PG8_WAIT_L(0); PG8_BAR; PG8_MMA(0, 0, At, B0); PG8_MMA(0, 1, At, B1); PG8_BAR; PG8_SCHED;
;             PG8_LDA(At, 0, 1); PG8_STAGE(PG8_SB(0, 0), b2, voffB); PG8_STAGE(PG8_SB(0, 1), b2 + hstepB, voffB); PG8_STAGE(PG8_SA(0, 0), a2, voffA);
;             PG8_WAIT_V(8); PG8_WAIT_L(0); PG8_BAR; PG8_MMA(1, 0, At, B0); PG8_MMA(1, 1, At, B1); PG8_BAR; PG8_SCHED;
.LBB0_1575:
	s_ashr_i32 s25, s24, 31
	s_lshl_b64 s[26:27], s[24:25], 20
	s_add_u32 s26, s94, s26
	s_addc_u32 s27, s95, s27
	s_and_b64 s[28:29], s[6:7], exec
	s_cselect_b32 s9, s27, s31
	s_cselect_b32 s25, s26, s30
	s_ashr_i32 s23, s22, 31
	s_lshl_b64 s[28:29], s[22:23], 19
	v_readlane_b32 s36, v252, 7
	v_readlane_b32 s37, v252, 8
	s_add_u32 s28, s36, s28
	s_addc_u32 s29, s37, s29
	s_and_b64 s[36:37], s[6:7], exec
	s_cselect_b32 s23, s29, s35
	s_cselect_b32 s64, s28, s34
	s_add_u32 s30, s30, 0x80080
	s_addc_u32 s31, s31, 0
	s_add_u32 s65, s34, 0x100
	s_addc_u32 s66, s35, 0
	s_mov_b32 s67, -2
	s_waitcnt lgkmcnt(0)
.LBB0_1576:
	ds_read_b128 v[106:109], v211
	ds_read_b128 v[114:117], v211 offset:1024
	ds_read_b128 v[130:133], v211 offset:2048
	ds_read_b128 v[134:137], v211 offset:3072
	ds_read_b128 v[146:149], v212
	ds_read_b128 v[150:153], v212 offset:1024
	ds_read_b128 v[154:157], v212 offset:2048
	ds_read_b128 v[158:161], v212 offset:3072
	s_add_u32 s34, s30, 0xfff80080
	s_addc_u32 s35, s31, -1
	s_cmp_eq_u32 s67, 12
	s_cselect_b32 s37, s9, s35
	s_cselect_b32 s36, s25, s34
	s_cselect_b32 s35, s23, s66
	s_cselect_b32 s34, s64, s65
	v_lshl_add_u64 v[206:207], s[30:31], 0, v[196:197]
	s_add_i32 m0, s33, 0xc000
	ds_read_b128 v[162:165], v213
	ds_read_b128 v[166:169], v213 offset:1024
	ds_read_b128 v[170:173], v213 offset:2048
	ds_read_b128 v[174:177], v213 offset:3072
	ds_read_b128 v[178:181], v213 offset:4096
	ds_read_b128 v[182:185], v213 offset:5120
	ds_read_b128 v[216:219], v213 offset:6144
	ds_read_b128 v[220:223], v213 offset:7168
	global_load_lds_dwordx4 v[206:207], off
	v_lshl_add_u64 v[206:207], s[30:31], 0, v[200:201]
	s_add_i32 m0, s33, 0xe000
	s_nop 0
	global_load_lds_dwordx4 v[206:207], off
	s_waitcnt vmcnt(8)
	s_waitcnt lgkmcnt(0)
	s_cmp_eq_u32 s67, -2
	s_cbranch_scc1 .Lcz_p8_0
	s_barrier
	s_setprio 1
	s_waitcnt lgkmcnt(0)
	v_mfma_f32_16x16x32_bf16 v[142:145], v[106:109], v[162:165], v[142:145]
	v_mfma_f32_16x16x32_bf16 v[138:141], v[130:133], v[162:165], v[138:141]
	v_mfma_f32_16x16x32_bf16 v[118:121], v[106:109], v[170:173], v[118:121]
	v_mfma_f32_16x16x32_bf16 v[110:113], v[130:133], v[170:173], v[110:113]
	v_mfma_f32_16x16x32_bf16 v[94:97], v[106:109], v[178:181], v[94:97]
	v_mfma_f32_16x16x32_bf16 v[90:93], v[130:133], v[178:181], v[90:93]
	v_mfma_f32_16x16x32_bf16 v[78:81], v[106:109], v[216:219], v[78:81]
	v_mfma_f32_16x16x32_bf16 v[74:77], v[130:133], v[216:219], v[74:77]
	v_mfma_f32_16x16x32_bf16 v[142:145], v[114:117], v[166:169], v[142:145]
	v_mfma_f32_16x16x32_bf16 v[138:141], v[134:137], v[166:169], v[138:141]
	v_mfma_f32_16x16x32_bf16 v[118:121], v[114:117], v[174:177], v[118:121]
	v_mfma_f32_16x16x32_bf16 v[110:113], v[134:137], v[174:177], v[110:113]
	v_mfma_f32_16x16x32_bf16 v[94:97], v[114:117], v[182:185], v[94:97]
	v_mfma_f32_16x16x32_bf16 v[90:93], v[134:137], v[182:185], v[90:93]
	v_mfma_f32_16x16x32_bf16 v[78:81], v[114:117], v[220:223], v[78:81]
	v_mfma_f32_16x16x32_bf16 v[74:77], v[134:137], v[220:223], v[74:77]
	s_setprio 0
	s_setprio 1
	v_mfma_f32_16x16x32_bf16 v[126:129], v[146:149], v[162:165], v[126:129]
	v_mfma_f32_16x16x32_bf16 v[122:125], v[154:157], v[162:165], v[122:125]
	v_mfma_f32_16x16x32_bf16 v[102:105], v[146:149], v[170:173], v[102:105]
	v_mfma_f32_16x16x32_bf16 v[98:101], v[154:157], v[170:173], v[98:101]
	v_mfma_f32_16x16x32_bf16 v[86:89], v[146:149], v[178:181], v[86:89]
	v_mfma_f32_16x16x32_bf16 v[82:85], v[154:157], v[178:181], v[82:85]
	v_mfma_f32_16x16x32_bf16 v[70:73], v[146:149], v[216:219], v[70:73]
	v_mfma_f32_16x16x32_bf16 v[66:69], v[154:157], v[216:219], v[66:69]
	v_mfma_f32_16x16x32_bf16 v[126:129], v[150:153], v[166:169], v[126:129]
	v_mfma_f32_16x16x32_bf16 v[122:125], v[158:161], v[166:169], v[122:125]
	v_mfma_f32_16x16x32_bf16 v[102:105], v[150:153], v[174:177], v[102:105]
	v_mfma_f32_16x16x32_bf16 v[98:101], v[158:161], v[174:177], v[98:101]
	v_mfma_f32_16x16x32_bf16 v[86:89], v[150:153], v[182:185], v[86:89]
	v_mfma_f32_16x16x32_bf16 v[82:85], v[158:161], v[182:185], v[82:85]
	v_mfma_f32_16x16x32_bf16 v[70:73], v[150:153], v[220:223], v[70:73]
	v_mfma_f32_16x16x32_bf16 v[66:69], v[158:161], v[220:223], v[66:69]
.Lcz_p8_0_j:
	s_setprio 0
	s_barrier
	s_add_i32 s72, s57, s3
	v_lshl_add_u64 v[206:207], s[34:35], 0, v[188:189]
	s_mov_b32 m0, s72
	ds_read_b128 v[162:165], v213 offset:16384
	ds_read_b128 v[166:169], v213 offset:17408
	ds_read_b128 v[170:173], v213 offset:18432
	ds_read_b128 v[174:177], v213 offset:19456
	ds_read_b128 v[178:181], v213 offset:20480
	ds_read_b128 v[182:185], v213 offset:21504
	ds_read_b128 v[216:219], v213 offset:22528
	ds_read_b128 v[220:223], v213 offset:23552
	global_load_lds_dwordx4 v[206:207], off
	s_add_i32 m0, s72, 0x2000
	s_add_u32 s72, s34, 0x40000
	v_lshl_add_u64 v[224:225], s[34:35], 0, v[192:193]
	s_addc_u32 s73, s35, 0
	s_add_i32 s74, s58, s3
	global_load_lds_dwordx4 v[224:225], off
	v_lshl_add_u64 v[226:227], s[72:73], 0, v[188:189]
	s_mov_b32 m0, s74
	v_lshl_add_u64 v[228:229], s[36:37], 0, v[190:191]
	global_load_lds_dwordx4 v[226:227], off
	v_lshl_add_u64 v[226:227], s[72:73], 0, v[192:193]
	s_add_i32 m0, s74, 0x2000
	s_nop 0
	global_load_lds_dwordx4 v[226:227], off
	v_lshl_add_u64 v[226:227], s[36:37], 0, v[186:187]
	s_mov_b32 m0, s33
	s_nop 0
	global_load_lds_dwordx4 v[226:227], off
	s_mov_b32 m0, s38
	s_nop 0
	global_load_lds_dwordx4 v[228:229], off
	s_waitcnt vmcnt(8)
	s_waitcnt lgkmcnt(0)
	s_cmp_eq_u32 s67, -2
	s_cbranch_scc1 .Lcz_p8_1
	s_barrier
; #define PG8_STAGE(bufoff, gbase, voff) do { _Pragma("unroll") for (int _i = 0; _i < 2; ++_i) \
;         __builtin_amdgcn_global_load_lds((const unsigned*)((const char*)(gbase) + (voff)[_i]), (LAS unsigned*)(lds + (bufoff) + ldsw + _i * 8192), 16, 0, 0); } while (0)
; #define PG8_LDA(dst, b, h) do { _Pragma("unroll") for (int m = 0; m < 4; ++m) _Pragma("unroll") for (int k = 0; k < 2; ++k) dst[m][k] = *(const LAS bf16x8*)(lds + PG8_SA(b, h) + aoff + m * 2048 + k * 1024); } while (0)
; #define PG8_LDB(dst, b, h) do { _Pragma("unroll") for (int n = 0; n < 2; ++n) _Pragma("unroll") for (int k = 0; k < 2; ++k) dst[n][k] = *(const LAS bf16x8*)(lds + PG8_SB(b, h) + boff + n * 2048 + k * 1024); } while (0)
; #define PG8_MMA(ai, bj, At, Bt) do { __builtin_amdgcn_s_setprio(1); _Pragma("unroll") for (int m = 0; m < 4; ++m) _Pragma("unroll") for (int n = 0; n < 2; ++n) _Pragma("unroll") for (int k = 0; k < 2; ++k) \
;         acc[ai][bj][m][n] = __builtin_amdgcn_mfma_f32_16x16x32_bf16(Bt[n][k], At[m][k], acc[ai][bj][m][n], 0, 0, 0); __builtin_amdgcn_s_setprio(0); } while (0)
; #define PG8_WAIT_V(n) asm volatile("s_waitcnt vmcnt(" #n ")" ::: "memory")
; #define PG8_WAIT_L(n) asm volatile("s_waitcnt lgkmcnt(" #n ")" ::: "memory")
; #define PG8_BAR __builtin_amdgcn_s_barrier()
; #define PG8_SCHED __builtin_amdgcn_sched_barrier(0)
; template <class Epi>
; __device__ __forceinline__ void gemm_phase(LAS unsigned char* lds, const Gemm g, const Sched& S, const Epi& E) {
;     ...
;             PG8_WAIT_V(8); PG8_WAIT_L(0); PG8_BAR; PG8_MMA(1, 0, At, B0); PG8_MMA(1, 1, At, B1); PG8_BAR; PG8_SCHED;
;             PG8_LDB(B0, 1, 0); PG8_LDB(B1, 1, 1); PG8_SCHED; PG8_LDA(At, 1, 0); PG8_STAGE(PG8_SA(0, 1), a2 + hstepA, voffA);
;             PG8_WAIT_V(8); PG8_WAIT_L(0); PG8_BAR; PG8_MMA(0, 0, At, B0); PG8_MMA(0, 1, At, B1); PG8_BAR; PG8_SCHED;
	s_setprio 1
	s_waitcnt lgkmcnt(0)
	v_mfma_f32_16x16x32_bf16 v[62:65], v[106:109], v[162:165], v[62:65]
	v_mfma_f32_16x16x32_bf16 v[58:61], v[130:133], v[162:165], v[58:61]
	v_mfma_f32_16x16x32_bf16 v[46:49], v[106:109], v[170:173], v[46:49]
	v_mfma_f32_16x16x32_bf16 v[42:45], v[130:133], v[170:173], v[42:45]
	v_mfma_f32_16x16x32_bf16 v[30:33], v[106:109], v[178:181], v[30:33]
	v_mfma_f32_16x16x32_bf16 v[26:29], v[130:133], v[178:181], v[26:29]
	v_mfma_f32_16x16x32_bf16 v[14:17], v[106:109], v[216:219], v[14:17]
	v_mfma_f32_16x16x32_bf16 v[10:13], v[130:133], v[216:219], v[10:13]
	v_mfma_f32_16x16x32_bf16 v[62:65], v[114:117], v[166:169], v[62:65]
	v_mfma_f32_16x16x32_bf16 v[58:61], v[134:137], v[166:169], v[58:61]
	v_mfma_f32_16x16x32_bf16 v[46:49], v[114:117], v[174:177], v[46:49]
	v_mfma_f32_16x16x32_bf16 v[42:45], v[134:137], v[174:177], v[42:45]
	v_mfma_f32_16x16x32_bf16 v[30:33], v[114:117], v[182:185], v[30:33]
	v_mfma_f32_16x16x32_bf16 v[26:29], v[134:137], v[182:185], v[26:29]
	v_mfma_f32_16x16x32_bf16 v[14:17], v[114:117], v[220:223], v[14:17]
	v_mfma_f32_16x16x32_bf16 v[10:13], v[134:137], v[220:223], v[10:13]
	s_setprio 0
	s_setprio 1
	v_mfma_f32_16x16x32_bf16 v[54:57], v[146:149], v[162:165], v[54:57]
	v_mfma_f32_16x16x32_bf16 v[50:53], v[154:157], v[162:165], v[50:53]
	v_mfma_f32_16x16x32_bf16 v[38:41], v[146:149], v[170:173], v[38:41]
	v_mfma_f32_16x16x32_bf16 v[34:37], v[154:157], v[170:173], v[34:37]
	v_mfma_f32_16x16x32_bf16 v[22:25], v[146:149], v[178:181], v[22:25]
	v_mfma_f32_16x16x32_bf16 v[18:21], v[154:157], v[178:181], v[18:21]
	v_mfma_f32_16x16x32_bf16 v[6:9], v[146:149], v[216:219], v[6:9]
	v_mfma_f32_16x16x32_bf16 v[2:5], v[154:157], v[216:219], v[2:5]
	v_mfma_f32_16x16x32_bf16 v[54:57], v[150:153], v[166:169], v[54:57]
	v_mfma_f32_16x16x32_bf16 v[50:53], v[158:161], v[166:169], v[50:53]
	v_mfma_f32_16x16x32_bf16 v[38:41], v[150:153], v[174:177], v[38:41]
	v_mfma_f32_16x16x32_bf16 v[34:37], v[158:161], v[174:177], v[34:37]
	v_mfma_f32_16x16x32_bf16 v[22:25], v[150:153], v[182:185], v[22:25]
	v_mfma_f32_16x16x32_bf16 v[18:21], v[158:161], v[182:185], v[18:21]
	v_mfma_f32_16x16x32_bf16 v[6:9], v[150:153], v[220:223], v[6:9]
	v_mfma_f32_16x16x32_bf16 v[2:5], v[158:161], v[220:223], v[2:5]
.Lcz_p8_1_j:
	s_setprio 0
	s_barrier
	s_add_i32 s72, 0, 0x18000
	s_add_i32 s73, 0, 0x1c000
	v_add_u32_e32 v134, s72, v210
	v_add_u32_e32 v158, s73, v210
	ds_read_b128 v[106:109], v134
	ds_read_b128 v[114:117], v134 offset:1024
	ds_read_b128 v[130:133], v134 offset:2048
	ds_read_b128 v[134:137], v134 offset:3072
	ds_read_b128 v[146:149], v158
	ds_read_b128 v[150:153], v158 offset:1024
	ds_read_b128 v[154:157], v158 offset:2048
	ds_read_b128 v[158:161], v158 offset:3072
	s_add_u32 s36, s36, 0x80000
	s_addc_u32 s37, s37, 0
	s_mov_b32 m0, s39
	v_lshl_add_u64 v[230:231], s[36:37], 0, v[186:187]
	ds_read_b128 v[162:165], v213 offset:32768
	ds_read_b128 v[166:169], v213 offset:33792
	ds_read_b128 v[170:173], v213 offset:34816
	ds_read_b128 v[174:177], v213 offset:35840
	ds_read_b128 v[178:181], v213 offset:36864
	ds_read_b128 v[182:185], v213 offset:37888
	ds_read_b128 v[216:219], v213 offset:38912
	ds_read_b128 v[220:223], v213 offset:39936
	global_load_lds_dwordx4 v[230:231], off
	v_lshl_add_u64 v[230:231], s[36:37], 0, v[190:191]
	s_mov_b32 m0, s42
	s_nop 0
	global_load_lds_dwordx4 v[230:231], off
	s_waitcnt vmcnt(8)
	s_waitcnt lgkmcnt(0)
	s_barrier
	s_setprio 1
	s_waitcnt lgkmcnt(0)
	v_mfma_f32_16x16x32_bf16 v[142:145], v[106:109], v[162:165], v[142:145]
	v_mfma_f32_16x16x32_bf16 v[138:141], v[130:133], v[162:165], v[138:141]
	v_mfma_f32_16x16x32_bf16 v[118:121], v[106:109], v[170:173], v[118:121]
	v_mfma_f32_16x16x32_bf16 v[110:113], v[130:133], v[170:173], v[110:113]
	v_mfma_f32_16x16x32_bf16 v[94:97], v[106:109], v[178:181], v[94:97]
	v_mfma_f32_16x16x32_bf16 v[90:93], v[130:133], v[178:181], v[90:93]
	v_mfma_f32_16x16x32_bf16 v[78:81], v[106:109], v[216:219], v[78:81]
	v_mfma_f32_16x16x32_bf16 v[74:77], v[130:133], v[216:219], v[74:77]
	v_mfma_f32_16x16x32_bf16 v[142:145], v[114:117], v[166:169], v[142:145]
	v_mfma_f32_16x16x32_bf16 v[138:141], v[134:137], v[166:169], v[138:141]
	v_mfma_f32_16x16x32_bf16 v[118:121], v[114:117], v[174:177], v[118:121]
	v_mfma_f32_16x16x32_bf16 v[110:113], v[134:137], v[174:177], v[110:113]
	v_mfma_f32_16x16x32_bf16 v[94:97], v[114:117], v[182:185], v[94:97]
	v_mfma_f32_16x16x32_bf16 v[90:93], v[134:137], v[182:185], v[90:93]
	v_mfma_f32_16x16x32_bf16 v[78:81], v[114:117], v[220:223], v[78:81]
	v_mfma_f32_16x16x32_bf16 v[74:77], v[134:137], v[220:223], v[74:77]
	s_setprio 0
	s_setprio 1
	v_mfma_f32_16x16x32_bf16 v[126:129], v[146:149], v[162:165], v[126:129]
	v_mfma_f32_16x16x32_bf16 v[122:125], v[154:157], v[162:165], v[122:125]
	v_mfma_f32_16x16x32_bf16 v[102:105], v[146:149], v[170:173], v[102:105]
	v_mfma_f32_16x16x32_bf16 v[98:101], v[154:157], v[170:173], v[98:101]
	v_mfma_f32_16x16x32_bf16 v[86:89], v[146:149], v[178:181], v[86:89]
	v_mfma_f32_16x16x32_bf16 v[82:85], v[154:157], v[178:181], v[82:85]
	v_mfma_f32_16x16x32_bf16 v[70:73], v[146:149], v[216:219], v[70:73]
	v_mfma_f32_16x16x32_bf16 v[66:69], v[154:157], v[216:219], v[66:69]
	v_mfma_f32_16x16x32_bf16 v[126:129], v[150:153], v[166:169], v[126:129]
	v_mfma_f32_16x16x32_bf16 v[122:125], v[158:161], v[166:169], v[122:125]
	v_mfma_f32_16x16x32_bf16 v[102:105], v[150:153], v[174:177], v[102:105]
	v_mfma_f32_16x16x32_bf16 v[98:101], v[158:161], v[174:177], v[98:101]
	v_mfma_f32_16x16x32_bf16 v[86:89], v[150:153], v[182:185], v[86:89]
	v_mfma_f32_16x16x32_bf16 v[82:85], v[158:161], v[182:185], v[82:85]
	v_mfma_f32_16x16x32_bf16 v[70:73], v[150:153], v[220:223], v[70:73]
	v_mfma_f32_16x16x32_bf16 v[66:69], v[158:161], v[220:223], v[66:69]
	s_setprio 0
	s_barrier
; #define PG8_STAGE(bufoff, gbase, voff) do { _Pragma("unroll") for (int _i = 0; _i < 2; ++_i) \
;         __builtin_amdgcn_global_load_lds((const unsigned*)((const char*)(gbase) + (voff)[_i]), (LAS unsigned*)(lds + (bufoff) + ldsw + _i * 8192), 16, 0, 0); } while (0)
; #define PG8_LDA(dst, b, h) do { _Pragma("unroll") for (int m = 0; m < 4; ++m) _Pragma("unroll") for (int k = 0; k < 2; ++k) dst[m][k] = *(const LAS bf16x8*)(lds + PG8_SA(b, h) + aoff + m * 2048 + k * 1024); } while (0)
; #define PG8_MMA(ai, bj, At, Bt) do { __builtin_amdgcn_s_setprio(1); _Pragma("unroll") for (int m = 0; m < 4; ++m) _Pragma("unroll") for (int n = 0; n < 2; ++n) _Pragma("unroll") for (int k = 0; k < 2; ++k) \
;         acc[ai][bj][m][n] = __builtin_amdgcn_mfma_f32_16x16x32_bf16(Bt[n][k], At[m][k], acc[ai][bj][m][n], 0, 0, 0); __builtin_amdgcn_s_setprio(0); } while (0)
; #define PG8_WAIT_V(n) asm volatile("s_waitcnt vmcnt(" #n ")" ::: "memory")
; #define PG8_WAIT_L(n) asm volatile("s_waitcnt lgkmcnt(" #n ")" ::: "memory")
; #define PG8_BAR __builtin_amdgcn_s_barrier()
; #define PG8_SCHED __builtin_amdgcn_sched_barrier(0)
; template <class Epi>
; __device__ __forceinline__ void gemm_phase(LAS unsigned char* lds, const Gemm g, const Sched& S, const Epi& E) {
;     ...
;             PG8_LDA(At, 1, 1); PG8_STAGE(PG8_SB(1, 0), b3, voffB); PG8_STAGE(PG8_SB(1, 1), b3 + hstepB, voffB); PG8_STAGE(PG8_SA(1, 0), a3, voffA);
;             PG8_WAIT_V(8); PG8_WAIT_L(0); PG8_BAR; PG8_MMA(1, 0, At, B0); PG8_MMA(1, 1, At, B1); PG8_BAR; PG8_SCHED;
;         }
;         if (wr == 0) PG8_BAR;
	s_add_i32 s36, s72, s3
	v_lshl_add_u64 v[206:207], v[206:207], 0, s[18:19]
	s_mov_b32 m0, s36
	ds_read_b128 v[162:165], v213 offset:49152
	ds_read_b128 v[166:169], v213 offset:50176
	ds_read_b128 v[170:173], v213 offset:51200
	ds_read_b128 v[174:177], v213 offset:52224
	ds_read_b128 v[178:181], v213 offset:53248
	ds_read_b128 v[182:185], v213 offset:54272
	ds_read_b128 v[216:219], v213 offset:55296
	ds_read_b128 v[220:223], v213 offset:56320
	global_load_lds_dwordx4 v[206:207], off
	s_add_i32 m0, s36, 0x2000
	s_add_u32 s34, s34, 0x40080
	v_lshl_add_u64 v[206:207], v[224:225], 0, s[18:19]
	s_addc_u32 s35, s35, 0
	s_add_i32 s36, s73, s3
	global_load_lds_dwordx4 v[206:207], off
	v_lshl_add_u64 v[206:207], s[34:35], 0, v[188:189]
	s_mov_b32 m0, s36
	s_nop 0
	global_load_lds_dwordx4 v[206:207], off
	v_lshl_add_u64 v[206:207], s[34:35], 0, v[192:193]
	s_add_i32 m0, s36, 0x2000
	s_nop 0
	global_load_lds_dwordx4 v[206:207], off
	v_lshl_add_u64 v[206:207], v[226:227], 0, s[18:19]
	s_mov_b32 m0, s45
	s_nop 0
	global_load_lds_dwordx4 v[206:207], off
	v_lshl_add_u64 v[206:207], v[228:229], 0, s[18:19]
	s_mov_b32 m0, s52
	s_nop 0
	global_load_lds_dwordx4 v[206:207], off
	s_waitcnt vmcnt(8)
	s_waitcnt lgkmcnt(0)
	s_barrier
	s_setprio 1
	s_waitcnt lgkmcnt(0)
	v_mfma_f32_16x16x32_bf16 v[62:65], v[106:109], v[162:165], v[62:65]
	v_mfma_f32_16x16x32_bf16 v[58:61], v[130:133], v[162:165], v[58:61]
	v_mfma_f32_16x16x32_bf16 v[46:49], v[106:109], v[170:173], v[46:49]
	v_mfma_f32_16x16x32_bf16 v[42:45], v[130:133], v[170:173], v[42:45]
	v_mfma_f32_16x16x32_bf16 v[30:33], v[106:109], v[178:181], v[30:33]
	v_mfma_f32_16x16x32_bf16 v[26:29], v[130:133], v[178:181], v[26:29]
	v_mfma_f32_16x16x32_bf16 v[14:17], v[106:109], v[216:219], v[14:17]
	v_mfma_f32_16x16x32_bf16 v[10:13], v[130:133], v[216:219], v[10:13]
	v_mfma_f32_16x16x32_bf16 v[62:65], v[114:117], v[166:169], v[62:65]
	v_mfma_f32_16x16x32_bf16 v[58:61], v[134:137], v[166:169], v[58:61]
	v_mfma_f32_16x16x32_bf16 v[46:49], v[114:117], v[174:177], v[46:49]
	v_mfma_f32_16x16x32_bf16 v[42:45], v[134:137], v[174:177], v[42:45]
	v_mfma_f32_16x16x32_bf16 v[30:33], v[114:117], v[182:185], v[30:33]
	v_mfma_f32_16x16x32_bf16 v[26:29], v[134:137], v[182:185], v[26:29]
	v_mfma_f32_16x16x32_bf16 v[14:17], v[114:117], v[220:223], v[14:17]
	v_mfma_f32_16x16x32_bf16 v[10:13], v[134:137], v[220:223], v[10:13]
	s_setprio 0
	s_setprio 1
	v_mfma_f32_16x16x32_bf16 v[54:57], v[146:149], v[162:165], v[54:57]
	v_mfma_f32_16x16x32_bf16 v[50:53], v[154:157], v[162:165], v[50:53]
	v_mfma_f32_16x16x32_bf16 v[38:41], v[146:149], v[170:173], v[38:41]
	v_mfma_f32_16x16x32_bf16 v[34:37], v[154:157], v[170:173], v[34:37]
	v_mfma_f32_16x16x32_bf16 v[22:25], v[146:149], v[178:181], v[22:25]
	v_mfma_f32_16x16x32_bf16 v[18:21], v[154:157], v[178:181], v[18:21]
	v_mfma_f32_16x16x32_bf16 v[6:9], v[146:149], v[216:219], v[6:9]
	v_mfma_f32_16x16x32_bf16 v[2:5], v[154:157], v[216:219], v[2:5]
	v_mfma_f32_16x16x32_bf16 v[54:57], v[150:153], v[166:169], v[54:57]
	v_mfma_f32_16x16x32_bf16 v[50:53], v[158:161], v[166:169], v[50:53]
	v_mfma_f32_16x16x32_bf16 v[38:41], v[150:153], v[174:177], v[38:41]
	v_mfma_f32_16x16x32_bf16 v[34:37], v[158:161], v[174:177], v[34:37]
	v_mfma_f32_16x16x32_bf16 v[22:25], v[150:153], v[182:185], v[22:25]
	v_mfma_f32_16x16x32_bf16 v[18:21], v[158:161], v[182:185], v[18:21]
	v_mfma_f32_16x16x32_bf16 v[6:9], v[150:153], v[220:223], v[6:9]
	v_mfma_f32_16x16x32_bf16 v[2:5], v[158:161], v[220:223], v[2:5]
	s_setprio 0
	s_barrier
	s_add_i32 s67, s67, 2
	s_add_u32 s30, s30, 0x100
	s_addc_u32 s31, s31, 0
	s_add_u32 s65, s65, 0x100
	s_addc_u32 s66, s66, 0
	s_cmp_gt_u32 s67, 13
	s_cbranch_scc0 .LBB0_1576
	s_and_b64 vcc, exec, s[20:21]
	s_cbranch_vccz .LBB0_1579
	s_barrier

; #define PG8_STAGE(bufoff, gbase, voff) do { _Pragma("unroll") for (int _i = 0; _i < 2; ++_i) \
;         __builtin_amdgcn_global_load_lds((const unsigned*)((const char*)(gbase) + (voff)[_i]), (LAS unsigned*)(lds + (bufoff) + ldsw + _i * 8192), 16, 0, 0); } while (0)
; #define PG8_LDA(dst, b, h) do { _Pragma("unroll") for (int m = 0; m < 4; ++m) _Pragma("unroll") for (int k = 0; k < 2; ++k) dst[m][k] = *(const LAS bf16x8*)(lds + PG8_SA(b, h) + aoff + m * 2048 + k * 1024); } while (0)
; #define PG8_MMA(ai, bj, At, Bt) do { __builtin_amdgcn_s_setprio(1); _Pragma("unroll") for (int m = 0; m < 4; ++m) _Pragma("unroll") for (int n = 0; n < 2; ++n) _Pragma("unroll") for (int k = 0; k < 2; ++k) \
;         acc[ai][bj][m][n] = __builtin_amdgcn_mfma_f32_16x16x32_bf16(Bt[n][k], At[m][k], acc[ai][bj][m][n], 0, 0, 0); __builtin_amdgcn_s_setprio(0); } while (0)
; #define PG8_WAIT_V(n) asm volatile("s_waitcnt vmcnt(" #n ")" ::: "memory")
; #define PG8_WAIT_L(n) asm volatile("s_waitcnt lgkmcnt(" #n ")" ::: "memory")
; #define PG8_BAR __builtin_amdgcn_s_barrier()
; #define PG8_SCHED __builtin_amdgcn_sched_barrier(0)
; template <class Epi>
; __device__ __forceinline__ void gemm_phase(LAS unsigned char* lds, const Gemm g, const Sched& S, const Epi& E) {
;     ...
;             PG8_WAIT_V(8); PG8_WAIT_L(0); PG8_BAR; PG8_MMA(0, 0, At, B0); PG8_MMA(0, 1, At, B1); PG8_BAR; PG8_SCHED;
;             PG8_LDA(At, 0, 1); PG8_STAGE(PG8_SB(0, 0), b2, voffB); PG8_STAGE(PG8_SB(0, 1), b2 + hstepB, voffB); PG8_STAGE(PG8_SA(0, 0), a2, voffA);
;             PG8_WAIT_V(8); PG8_WAIT_L(0); PG8_BAR; PG8_MMA(1, 0, At, B0); PG8_MMA(1, 1, At, B1); PG8_BAR; PG8_SCHED;
.Lcz_p8_0:
	s_barrier
	s_setprio 1
	s_waitcnt lgkmcnt(0)
	v_mfma_f32_16x16x32_bf16 v[142:145], v[106:109], v[162:165], 0
	v_mfma_f32_16x16x32_bf16 v[138:141], v[130:133], v[162:165], 0
	v_mfma_f32_16x16x32_bf16 v[118:121], v[106:109], v[170:173], 0
	v_mfma_f32_16x16x32_bf16 v[110:113], v[130:133], v[170:173], 0
	v_mfma_f32_16x16x32_bf16 v[94:97], v[106:109], v[178:181], 0
	v_mfma_f32_16x16x32_bf16 v[90:93], v[130:133], v[178:181], 0
	v_mfma_f32_16x16x32_bf16 v[78:81], v[106:109], v[216:219], 0
	v_mfma_f32_16x16x32_bf16 v[74:77], v[130:133], v[216:219], 0
	v_mfma_f32_16x16x32_bf16 v[142:145], v[114:117], v[166:169], v[142:145]
	v_mfma_f32_16x16x32_bf16 v[138:141], v[134:137], v[166:169], v[138:141]
	v_mfma_f32_16x16x32_bf16 v[118:121], v[114:117], v[174:177], v[118:121]
	v_mfma_f32_16x16x32_bf16 v[110:113], v[134:137], v[174:177], v[110:113]
	v_mfma_f32_16x16x32_bf16 v[94:97], v[114:117], v[182:185], v[94:97]
	v_mfma_f32_16x16x32_bf16 v[90:93], v[134:137], v[182:185], v[90:93]
	v_mfma_f32_16x16x32_bf16 v[78:81], v[114:117], v[220:223], v[78:81]
	v_mfma_f32_16x16x32_bf16 v[74:77], v[134:137], v[220:223], v[74:77]
	s_setprio 0
	s_setprio 1
	v_mfma_f32_16x16x32_bf16 v[126:129], v[146:149], v[162:165], 0
	v_mfma_f32_16x16x32_bf16 v[122:125], v[154:157], v[162:165], 0
	v_mfma_f32_16x16x32_bf16 v[102:105], v[146:149], v[170:173], 0
	v_mfma_f32_16x16x32_bf16 v[98:101], v[154:157], v[170:173], 0
	v_mfma_f32_16x16x32_bf16 v[86:89], v[146:149], v[178:181], 0
	v_mfma_f32_16x16x32_bf16 v[82:85], v[154:157], v[178:181], 0
	v_mfma_f32_16x16x32_bf16 v[70:73], v[146:149], v[216:219], 0
	v_mfma_f32_16x16x32_bf16 v[66:69], v[154:157], v[216:219], 0
	v_mfma_f32_16x16x32_bf16 v[126:129], v[150:153], v[166:169], v[126:129]
	v_mfma_f32_16x16x32_bf16 v[122:125], v[158:161], v[166:169], v[122:125]
	v_mfma_f32_16x16x32_bf16 v[102:105], v[150:153], v[174:177], v[102:105]
	v_mfma_f32_16x16x32_bf16 v[98:101], v[158:161], v[174:177], v[98:101]
	v_mfma_f32_16x16x32_bf16 v[86:89], v[150:153], v[182:185], v[86:89]
	v_mfma_f32_16x16x32_bf16 v[82:85], v[158:161], v[182:185], v[82:85]
	v_mfma_f32_16x16x32_bf16 v[70:73], v[150:153], v[220:223], v[70:73]
	v_mfma_f32_16x16x32_bf16 v[66:69], v[158:161], v[220:223], v[66:69]
	s_branch .Lcz_p8_0_j
.Lcz_p8_1:
	s_barrier
	s_setprio 1
	s_waitcnt lgkmcnt(0)
	v_mfma_f32_16x16x32_bf16 v[62:65], v[106:109], v[162:165], 0
	v_mfma_f32_16x16x32_bf16 v[58:61], v[130:133], v[162:165], 0
	v_mfma_f32_16x16x32_bf16 v[46:49], v[106:109], v[170:173], 0
	v_mfma_f32_16x16x32_bf16 v[42:45], v[130:133], v[170:173], 0
	v_mfma_f32_16x16x32_bf16 v[30:33], v[106:109], v[178:181], 0
	v_mfma_f32_16x16x32_bf16 v[26:29], v[130:133], v[178:181], 0
	v_mfma_f32_16x16x32_bf16 v[14:17], v[106:109], v[216:219], 0
	v_mfma_f32_16x16x32_bf16 v[10:13], v[130:133], v[216:219], 0
	v_mfma_f32_16x16x32_bf16 v[62:65], v[114:117], v[166:169], v[62:65]
	v_mfma_f32_16x16x32_bf16 v[58:61], v[134:137], v[166:169], v[58:61]
	v_mfma_f32_16x16x32_bf16 v[46:49], v[114:117], v[174:177], v[46:49]
	v_mfma_f32_16x16x32_bf16 v[42:45], v[134:137], v[174:177], v[42:45]
	v_mfma_f32_16x16x32_bf16 v[30:33], v[114:117], v[182:185], v[30:33]
	v_mfma_f32_16x16x32_bf16 v[26:29], v[134:137], v[182:185], v[26:29]
	v_mfma_f32_16x16x32_bf16 v[14:17], v[114:117], v[220:223], v[14:17]
	v_mfma_f32_16x16x32_bf16 v[10:13], v[134:137], v[220:223], v[10:13]
	s_setprio 0
	s_setprio 1
	v_mfma_f32_16x16x32_bf16 v[54:57], v[146:149], v[162:165], 0
	v_mfma_f32_16x16x32_bf16 v[50:53], v[154:157], v[162:165], 0
	v_mfma_f32_16x16x32_bf16 v[38:41], v[146:149], v[170:173], 0
	v_mfma_f32_16x16x32_bf16 v[34:37], v[154:157], v[170:173], 0
	v_mfma_f32_16x16x32_bf16 v[22:25], v[146:149], v[178:181], 0
	v_mfma_f32_16x16x32_bf16 v[18:21], v[154:157], v[178:181], 0
	v_mfma_f32_16x16x32_bf16 v[6:9], v[146:149], v[216:219], 0
	v_mfma_f32_16x16x32_bf16 v[2:5], v[154:157], v[216:219], 0
	v_mfma_f32_16x16x32_bf16 v[54:57], v[150:153], v[166:169], v[54:57]
	v_mfma_f32_16x16x32_bf16 v[50:53], v[158:161], v[166:169], v[50:53]
	v_mfma_f32_16x16x32_bf16 v[38:41], v[150:153], v[174:177], v[38:41]
	v_mfma_f32_16x16x32_bf16 v[34:37], v[158:161], v[174:177], v[34:37]
	v_mfma_f32_16x16x32_bf16 v[22:25], v[150:153], v[182:185], v[22:25]
	v_mfma_f32_16x16x32_bf16 v[18:21], v[158:161], v[182:185], v[18:21]
	v_mfma_f32_16x16x32_bf16 v[6:9], v[150:153], v[220:223], v[6:9]
	v_mfma_f32_16x16x32_bf16 v[2:5], v[158:161], v[220:223], v[2:5]
	s_branch .Lcz_p8_1_j

; #define PG8_STAGE(bufoff, gbase, voff) do { _Pragma("unroll") for (int _i = 0; _i < 2; ++_i) \
;         __builtin_amdgcn_global_load_lds((const unsigned*)((const char*)(gbase) + (voff)[_i]), (LAS unsigned*)(lds + (bufoff) + ldsw + _i * 8192), 16, 0, 0); } while (0)
; #define PG8_LDA(dst, b, h) do { _Pragma("unroll") for (int m = 0; m < 4; ++m) _Pragma("unroll") for (int k = 0; k < 2; ++k) dst[m][k] = *(const LAS bf16x8*)(lds + PG8_SA(b, h) + aoff + m * 2048 + k * 1024); } while (0)
; #define PG8_LDB(dst, b, h) do { _Pragma("unroll") for (int n = 0; n < 2; ++n) _Pragma("unroll") for (int k = 0; k < 2; ++k) dst[n][k] = *(const LAS bf16x8*)(lds + PG8_SB(b, h) + boff + n * 2048 + k * 1024); } while (0)
; #define PG8_MMA(ai, bj, At, Bt) do { __builtin_amdgcn_s_setprio(1); _Pragma("unroll") for (int m = 0; m < 4; ++m) _Pragma("unroll") for (int n = 0; n < 2; ++n) _Pragma("unroll") for (int k = 0; k < 2; ++k) \
;         acc[ai][bj][m][n] = __builtin_amdgcn_mfma_f32_16x16x32_bf16(Bt[n][k], At[m][k], acc[ai][bj][m][n], 0, 0, 0); __builtin_amdgcn_s_setprio(0); } while (0)
; #define PG8_WAIT_V(n) asm volatile("s_waitcnt vmcnt(" #n ")" ::: "memory")
; #define PG8_WAIT_L(n) asm volatile("s_waitcnt lgkmcnt(" #n ")" ::: "memory")
; #define PG8_BAR __builtin_amdgcn_s_barrier()
; #define PG8_SCHED __builtin_amdgcn_sched_barrier(0)
; template <class Epi>
; __device__ __forceinline__ void gemm_phase(LAS unsigned char* lds, const Gemm g, const Sched& S, const Epi& E) {
;     ...
;     for (int a = 0; a < 2; ++a)
; #pragma unroll
;         for (int b = 0; b < 2; ++b)
; #pragma unroll
;             for (int m = 0; m < 4; ++m)
; #pragma unroll
;                 for (int n = 0; n < 2; ++n) acc[a][b][m][n] = (f32x4){0.f, 0.f, 0.f, 0.f};
;     ...
;             PG8_LDB(B0, 0, 0); PG8_LDB(B1, 0, 1); PG8_SCHED; PG8_LDA(At, 0, 0); PG8_STAGE(PG8_SA(1, 1), a1 + hstepA, voffA);
;             PG8_WAIT_V(8); PG8_WAIT_L(0); PG8_BAR; PG8_MMA(0, 0, At, B0); PG8_MMA(0, 1, At, B1); PG8_BAR; PG8_SCHED;
;             PG8_LDA(At, 0, 1); PG8_STAGE(PG8_SB(0, 0), b2, voffB); PG8_STAGE(PG8_SB(0, 1), b2 + hstepB, voffB); PG8_STAGE(PG8_SA(0, 0), a2, voffA);
;             PG8_WAIT_V(8); PG8_WAIT_L(0); PG8_BAR; PG8_MMA(1, 0, At, B0); PG8_MMA(1, 1, At, B1); PG8_BAR; PG8_SCHED;
.LBB0_1799:
	s_add_u32 s8, s34, 0xb0080
	s_addc_u32 s9, s35, 0
	s_add_u32 s73, s30, 0x100
	s_addc_u32 s74, s31, 0
	s_mov_b32 s75, -2
	s_waitcnt lgkmcnt(0)
.LBB0_1800:
	ds_read_b128 v[106:109], v210
	ds_read_b128 v[114:117], v210 offset:1024
	ds_read_b128 v[130:133], v210 offset:2048
	ds_read_b128 v[142:145], v210 offset:3072
	ds_read_b128 v[146:149], v211
	ds_read_b128 v[150:153], v211 offset:1024
	ds_read_b128 v[154:157], v211 offset:2048
	ds_read_b128 v[158:161], v211 offset:3072
	s_add_u32 s30, s8, 0xfff50080
	s_addc_u32 s31, s9, -1
	s_cmp_eq_u32 s75, 40
	s_cselect_b32 s35, s27, s31
	s_cselect_b32 s34, s26, s30
	s_cselect_b32 s31, s29, s74
	s_cselect_b32 s30, s28, s73
	v_lshl_add_u64 v[206:207], s[8:9], 0, v[196:197]
	s_add_i32 m0, s33, 0xc000
	ds_read_b128 v[162:165], v212
	ds_read_b128 v[166:169], v212 offset:1024
	ds_read_b128 v[170:173], v212 offset:2048
	ds_read_b128 v[174:177], v212 offset:3072
	ds_read_b128 v[178:181], v212 offset:4096
	ds_read_b128 v[182:185], v212 offset:5120
	ds_read_b128 v[214:217], v212 offset:6144
	ds_read_b128 v[218:221], v212 offset:7168
	global_load_lds_dwordx4 v[206:207], off
	v_lshl_add_u64 v[206:207], s[8:9], 0, v[200:201]
	s_add_i32 m0, s33, 0xe000
	s_nop 0
	global_load_lds_dwordx4 v[206:207], off
	s_waitcnt vmcnt(8)
	s_waitcnt lgkmcnt(0)
	s_cmp_eq_u32 s75, -2
	s_cbranch_scc1 .Lcz_p10_0
	s_barrier
	s_setprio 1
	s_waitcnt lgkmcnt(0)
	v_mfma_f32_16x16x32_bf16 v[138:141], v[106:109], v[162:165], v[138:141]
	v_mfma_f32_16x16x32_bf16 v[134:137], v[130:133], v[162:165], v[134:137]
	v_mfma_f32_16x16x32_bf16 v[118:121], v[106:109], v[170:173], v[118:121]
	v_mfma_f32_16x16x32_bf16 v[110:113], v[130:133], v[170:173], v[110:113]
	v_mfma_f32_16x16x32_bf16 v[94:97], v[106:109], v[178:181], v[94:97]
	v_mfma_f32_16x16x32_bf16 v[90:93], v[130:133], v[178:181], v[90:93]
	v_mfma_f32_16x16x32_bf16 v[78:81], v[106:109], v[214:217], v[78:81]
	v_mfma_f32_16x16x32_bf16 v[74:77], v[130:133], v[214:217], v[74:77]
	v_mfma_f32_16x16x32_bf16 v[138:141], v[114:117], v[166:169], v[138:141]
	v_mfma_f32_16x16x32_bf16 v[134:137], v[142:145], v[166:169], v[134:137]
	v_mfma_f32_16x16x32_bf16 v[118:121], v[114:117], v[174:177], v[118:121]
	v_mfma_f32_16x16x32_bf16 v[110:113], v[142:145], v[174:177], v[110:113]
	v_mfma_f32_16x16x32_bf16 v[94:97], v[114:117], v[182:185], v[94:97]
	v_mfma_f32_16x16x32_bf16 v[90:93], v[142:145], v[182:185], v[90:93]
	v_mfma_f32_16x16x32_bf16 v[78:81], v[114:117], v[218:221], v[78:81]
	v_mfma_f32_16x16x32_bf16 v[74:77], v[142:145], v[218:221], v[74:77]
	s_setprio 0
	s_setprio 1
	v_mfma_f32_16x16x32_bf16 v[126:129], v[146:149], v[162:165], v[126:129]
	v_mfma_f32_16x16x32_bf16 v[122:125], v[154:157], v[162:165], v[122:125]
	v_mfma_f32_16x16x32_bf16 v[102:105], v[146:149], v[170:173], v[102:105]
	v_mfma_f32_16x16x32_bf16 v[98:101], v[154:157], v[170:173], v[98:101]
	v_mfma_f32_16x16x32_bf16 v[86:89], v[146:149], v[178:181], v[86:89]
	v_mfma_f32_16x16x32_bf16 v[82:85], v[154:157], v[178:181], v[82:85]
	v_mfma_f32_16x16x32_bf16 v[70:73], v[146:149], v[214:217], v[70:73]
	v_mfma_f32_16x16x32_bf16 v[66:69], v[154:157], v[214:217], v[66:69]
	v_mfma_f32_16x16x32_bf16 v[126:129], v[150:153], v[166:169], v[126:129]
	v_mfma_f32_16x16x32_bf16 v[122:125], v[158:161], v[166:169], v[122:125]
	v_mfma_f32_16x16x32_bf16 v[102:105], v[150:153], v[174:177], v[102:105]
	v_mfma_f32_16x16x32_bf16 v[98:101], v[158:161], v[174:177], v[98:101]
	v_mfma_f32_16x16x32_bf16 v[86:89], v[150:153], v[182:185], v[86:89]
	v_mfma_f32_16x16x32_bf16 v[82:85], v[158:161], v[182:185], v[82:85]
	v_mfma_f32_16x16x32_bf16 v[70:73], v[150:153], v[218:221], v[70:73]
	v_mfma_f32_16x16x32_bf16 v[66:69], v[158:161], v[218:221], v[66:69]
.Lcz_p10_0_j:
	s_setprio 0
	s_barrier
	s_add_i32 s76, s53, s3
	v_lshl_add_u64 v[206:207], s[30:31], 0, v[188:189]
	s_mov_b32 m0, s76
	ds_read_b128 v[162:165], v212 offset:16384
	ds_read_b128 v[166:169], v212 offset:17408
	ds_read_b128 v[170:173], v212 offset:18432
	ds_read_b128 v[174:177], v212 offset:19456
	ds_read_b128 v[178:181], v212 offset:20480
	ds_read_b128 v[182:185], v212 offset:21504
	ds_read_b128 v[214:217], v212 offset:22528
	ds_read_b128 v[218:221], v212 offset:23552
	global_load_lds_dwordx4 v[206:207], off
	s_add_i32 m0, s76, 0x2000
	s_add_u32 s76, s30, 0xb0000
	v_lshl_add_u64 v[222:223], s[30:31], 0, v[192:193]
	s_addc_u32 s77, s31, 0
	s_add_i32 s78, s54, s3
	global_load_lds_dwordx4 v[222:223], off
	v_lshl_add_u64 v[224:225], s[76:77], 0, v[188:189]
	s_mov_b32 m0, s78
	v_lshl_add_u64 v[226:227], s[34:35], 0, v[190:191]
	global_load_lds_dwordx4 v[224:225], off
	v_lshl_add_u64 v[224:225], s[76:77], 0, v[192:193]
	s_add_i32 m0, s78, 0x2000
	s_nop 0
	global_load_lds_dwordx4 v[224:225], off
	v_lshl_add_u64 v[224:225], s[34:35], 0, v[186:187]
	s_mov_b32 m0, s33
	s_nop 0
	global_load_lds_dwordx4 v[224:225], off
	s_mov_b32 m0, s36
	s_nop 0
	global_load_lds_dwordx4 v[226:227], off
	s_waitcnt vmcnt(8)
	s_waitcnt lgkmcnt(0)
	s_cmp_eq_u32 s75, -2
	s_cbranch_scc1 .Lcz_p10_1
	s_barrier
; #define PG8_STAGE(bufoff, gbase, voff) do { _Pragma("unroll") for (int _i = 0; _i < 2; ++_i) \
;         __builtin_amdgcn_global_load_lds((const unsigned*)((const char*)(gbase) + (voff)[_i]), (LAS unsigned*)(lds + (bufoff) + ldsw + _i * 8192), 16, 0, 0); } while (0)
; #define PG8_LDA(dst, b, h) do { _Pragma("unroll") for (int m = 0; m < 4; ++m) _Pragma("unroll") for (int k = 0; k < 2; ++k) dst[m][k] = *(const LAS bf16x8*)(lds + PG8_SA(b, h) + aoff + m * 2048 + k * 1024); } while (0)
; #define PG8_LDB(dst, b, h) do { _Pragma("unroll") for (int n = 0; n < 2; ++n) _Pragma("unroll") for (int k = 0; k < 2; ++k) dst[n][k] = *(const LAS bf16x8*)(lds + PG8_SB(b, h) + boff + n * 2048 + k * 1024); } while (0)
; #define PG8_MMA(ai, bj, At, Bt) do { __builtin_amdgcn_s_setprio(1); _Pragma("unroll") for (int m = 0; m < 4; ++m) _Pragma("unroll") for (int n = 0; n < 2; ++n) _Pragma("unroll") for (int k = 0; k < 2; ++k) \
;         acc[ai][bj][m][n] = __builtin_amdgcn_mfma_f32_16x16x32_bf16(Bt[n][k], At[m][k], acc[ai][bj][m][n], 0, 0, 0); __builtin_amdgcn_s_setprio(0); } while (0)
; #define PG8_WAIT_V(n) asm volatile("s_waitcnt vmcnt(" #n ")" ::: "memory")
; #define PG8_WAIT_L(n) asm volatile("s_waitcnt lgkmcnt(" #n ")" ::: "memory")
; #define PG8_BAR __builtin_amdgcn_s_barrier()
; #define PG8_SCHED __builtin_amdgcn_sched_barrier(0)
; template <class Epi>
; __device__ __forceinline__ void gemm_phase(LAS unsigned char* lds, const Gemm g, const Sched& S, const Epi& E) {
;     ...
;             PG8_WAIT_V(8); PG8_WAIT_L(0); PG8_BAR; PG8_MMA(1, 0, At, B0); PG8_MMA(1, 1, At, B1); PG8_BAR; PG8_SCHED;
;             PG8_LDB(B0, 1, 0); PG8_LDB(B1, 1, 1); PG8_SCHED; PG8_LDA(At, 1, 0); PG8_STAGE(PG8_SA(0, 1), a2 + hstepA, voffA);
;             PG8_WAIT_V(8); PG8_WAIT_L(0); PG8_BAR; PG8_MMA(0, 0, At, B0); PG8_MMA(0, 1, At, B1); PG8_BAR; PG8_SCHED;
	s_setprio 1
	s_waitcnt lgkmcnt(0)
	v_mfma_f32_16x16x32_bf16 v[62:65], v[106:109], v[162:165], v[62:65]
	v_mfma_f32_16x16x32_bf16 v[58:61], v[130:133], v[162:165], v[58:61]
	v_mfma_f32_16x16x32_bf16 v[46:49], v[106:109], v[170:173], v[46:49]
	v_mfma_f32_16x16x32_bf16 v[42:45], v[130:133], v[170:173], v[42:45]
	v_mfma_f32_16x16x32_bf16 v[30:33], v[106:109], v[178:181], v[30:33]
	v_mfma_f32_16x16x32_bf16 v[26:29], v[130:133], v[178:181], v[26:29]
	v_mfma_f32_16x16x32_bf16 v[14:17], v[106:109], v[214:217], v[14:17]
	v_mfma_f32_16x16x32_bf16 v[10:13], v[130:133], v[214:217], v[10:13]
	v_mfma_f32_16x16x32_bf16 v[62:65], v[114:117], v[166:169], v[62:65]
	v_mfma_f32_16x16x32_bf16 v[58:61], v[142:145], v[166:169], v[58:61]
	v_mfma_f32_16x16x32_bf16 v[46:49], v[114:117], v[174:177], v[46:49]
	v_mfma_f32_16x16x32_bf16 v[42:45], v[142:145], v[174:177], v[42:45]
	v_mfma_f32_16x16x32_bf16 v[30:33], v[114:117], v[182:185], v[30:33]
	v_mfma_f32_16x16x32_bf16 v[26:29], v[142:145], v[182:185], v[26:29]
	v_mfma_f32_16x16x32_bf16 v[14:17], v[114:117], v[218:221], v[14:17]
	v_mfma_f32_16x16x32_bf16 v[10:13], v[142:145], v[218:221], v[10:13]
	s_setprio 0
	s_setprio 1
	v_mfma_f32_16x16x32_bf16 v[54:57], v[146:149], v[162:165], v[54:57]
	v_mfma_f32_16x16x32_bf16 v[50:53], v[154:157], v[162:165], v[50:53]
	v_mfma_f32_16x16x32_bf16 v[38:41], v[146:149], v[170:173], v[38:41]
	v_mfma_f32_16x16x32_bf16 v[34:37], v[154:157], v[170:173], v[34:37]
	v_mfma_f32_16x16x32_bf16 v[22:25], v[146:149], v[178:181], v[22:25]
	v_mfma_f32_16x16x32_bf16 v[18:21], v[154:157], v[178:181], v[18:21]
	v_mfma_f32_16x16x32_bf16 v[6:9], v[146:149], v[214:217], v[6:9]
	v_mfma_f32_16x16x32_bf16 v[2:5], v[154:157], v[214:217], v[2:5]
	v_mfma_f32_16x16x32_bf16 v[54:57], v[150:153], v[166:169], v[54:57]
	v_mfma_f32_16x16x32_bf16 v[50:53], v[158:161], v[166:169], v[50:53]
	v_mfma_f32_16x16x32_bf16 v[38:41], v[150:153], v[174:177], v[38:41]
	v_mfma_f32_16x16x32_bf16 v[34:37], v[158:161], v[174:177], v[34:37]
	v_mfma_f32_16x16x32_bf16 v[22:25], v[150:153], v[182:185], v[22:25]
	v_mfma_f32_16x16x32_bf16 v[18:21], v[158:161], v[182:185], v[18:21]
	v_mfma_f32_16x16x32_bf16 v[6:9], v[150:153], v[218:221], v[6:9]
	v_mfma_f32_16x16x32_bf16 v[2:5], v[158:161], v[218:221], v[2:5]
.Lcz_p10_1_j:
	s_setprio 0
	s_barrier
	s_add_i32 s76, 0, 0x18000
	s_add_i32 s77, 0, 0x1c000
	v_add_u32_e32 v142, s76, v209
	v_add_u32_e32 v158, s77, v209
	ds_read_b128 v[106:109], v142
	ds_read_b128 v[114:117], v142 offset:1024
	ds_read_b128 v[130:133], v142 offset:2048
	ds_read_b128 v[142:145], v142 offset:3072
	ds_read_b128 v[146:149], v158
	ds_read_b128 v[150:153], v158 offset:1024
	ds_read_b128 v[154:157], v158 offset:2048
	ds_read_b128 v[158:161], v158 offset:3072
	s_add_u32 s34, s34, 0xb0000
	s_addc_u32 s35, s35, 0
	s_mov_b32 m0, s37
	v_lshl_add_u64 v[228:229], s[34:35], 0, v[186:187]
	ds_read_b128 v[162:165], v212 offset:32768
	ds_read_b128 v[166:169], v212 offset:33792
	ds_read_b128 v[170:173], v212 offset:34816
	ds_read_b128 v[174:177], v212 offset:35840
	ds_read_b128 v[178:181], v212 offset:36864
	ds_read_b128 v[182:185], v212 offset:37888
	ds_read_b128 v[214:217], v212 offset:38912
	ds_read_b128 v[218:221], v212 offset:39936
	global_load_lds_dwordx4 v[228:229], off
	v_lshl_add_u64 v[228:229], s[34:35], 0, v[190:191]
	s_mov_b32 m0, s38
	s_nop 0
	global_load_lds_dwordx4 v[228:229], off
	s_waitcnt vmcnt(8)
	s_waitcnt lgkmcnt(0)
	s_barrier
	s_setprio 1
	s_waitcnt lgkmcnt(0)
	v_mfma_f32_16x16x32_bf16 v[138:141], v[106:109], v[162:165], v[138:141]
	v_mfma_f32_16x16x32_bf16 v[134:137], v[130:133], v[162:165], v[134:137]
	v_mfma_f32_16x16x32_bf16 v[118:121], v[106:109], v[170:173], v[118:121]
	v_mfma_f32_16x16x32_bf16 v[110:113], v[130:133], v[170:173], v[110:113]
	v_mfma_f32_16x16x32_bf16 v[94:97], v[106:109], v[178:181], v[94:97]
	v_mfma_f32_16x16x32_bf16 v[90:93], v[130:133], v[178:181], v[90:93]
	v_mfma_f32_16x16x32_bf16 v[78:81], v[106:109], v[214:217], v[78:81]
	v_mfma_f32_16x16x32_bf16 v[74:77], v[130:133], v[214:217], v[74:77]
	v_mfma_f32_16x16x32_bf16 v[138:141], v[114:117], v[166:169], v[138:141]
	v_mfma_f32_16x16x32_bf16 v[134:137], v[142:145], v[166:169], v[134:137]
	v_mfma_f32_16x16x32_bf16 v[118:121], v[114:117], v[174:177], v[118:121]
	v_mfma_f32_16x16x32_bf16 v[110:113], v[142:145], v[174:177], v[110:113]
	v_mfma_f32_16x16x32_bf16 v[94:97], v[114:117], v[182:185], v[94:97]
	v_mfma_f32_16x16x32_bf16 v[90:93], v[142:145], v[182:185], v[90:93]
	v_mfma_f32_16x16x32_bf16 v[78:81], v[114:117], v[218:221], v[78:81]
	v_mfma_f32_16x16x32_bf16 v[74:77], v[142:145], v[218:221], v[74:77]
	s_setprio 0
	s_setprio 1
	v_mfma_f32_16x16x32_bf16 v[126:129], v[146:149], v[162:165], v[126:129]
	v_mfma_f32_16x16x32_bf16 v[122:125], v[154:157], v[162:165], v[122:125]
	v_mfma_f32_16x16x32_bf16 v[102:105], v[146:149], v[170:173], v[102:105]
	v_mfma_f32_16x16x32_bf16 v[98:101], v[154:157], v[170:173], v[98:101]
	v_mfma_f32_16x16x32_bf16 v[86:89], v[146:149], v[178:181], v[86:89]
	v_mfma_f32_16x16x32_bf16 v[82:85], v[154:157], v[178:181], v[82:85]
	v_mfma_f32_16x16x32_bf16 v[70:73], v[146:149], v[214:217], v[70:73]
	v_mfma_f32_16x16x32_bf16 v[66:69], v[154:157], v[214:217], v[66:69]
	v_mfma_f32_16x16x32_bf16 v[126:129], v[150:153], v[166:169], v[126:129]
	v_mfma_f32_16x16x32_bf16 v[122:125], v[158:161], v[166:169], v[122:125]
	v_mfma_f32_16x16x32_bf16 v[102:105], v[150:153], v[174:177], v[102:105]
	v_mfma_f32_16x16x32_bf16 v[98:101], v[158:161], v[174:177], v[98:101]
	v_mfma_f32_16x16x32_bf16 v[86:89], v[150:153], v[182:185], v[86:89]
	v_mfma_f32_16x16x32_bf16 v[82:85], v[158:161], v[182:185], v[82:85]
	v_mfma_f32_16x16x32_bf16 v[70:73], v[150:153], v[218:221], v[70:73]
	v_mfma_f32_16x16x32_bf16 v[66:69], v[158:161], v[218:221], v[66:69]
	s_setprio 0
	s_barrier
; #define PG8_STAGE(bufoff, gbase, voff) do { _Pragma("unroll") for (int _i = 0; _i < 2; ++_i) \
;         __builtin_amdgcn_global_load_lds((const unsigned*)((const char*)(gbase) + (voff)[_i]), (LAS unsigned*)(lds + (bufoff) + ldsw + _i * 8192), 16, 0, 0); } while (0)
; #define PG8_LDA(dst, b, h) do { _Pragma("unroll") for (int m = 0; m < 4; ++m) _Pragma("unroll") for (int k = 0; k < 2; ++k) dst[m][k] = *(const LAS bf16x8*)(lds + PG8_SA(b, h) + aoff + m * 2048 + k * 1024); } while (0)
; #define PG8_MMA(ai, bj, At, Bt) do { __builtin_amdgcn_s_setprio(1); _Pragma("unroll") for (int m = 0; m < 4; ++m) _Pragma("unroll") for (int n = 0; n < 2; ++n) _Pragma("unroll") for (int k = 0; k < 2; ++k) \
;         acc[ai][bj][m][n] = __builtin_amdgcn_mfma_f32_16x16x32_bf16(Bt[n][k], At[m][k], acc[ai][bj][m][n], 0, 0, 0); __builtin_amdgcn_s_setprio(0); } while (0)
; #define PG8_WAIT_V(n) asm volatile("s_waitcnt vmcnt(" #n ")" ::: "memory")
; #define PG8_WAIT_L(n) asm volatile("s_waitcnt lgkmcnt(" #n ")" ::: "memory")
; #define PG8_BAR __builtin_amdgcn_s_barrier()
; #define PG8_SCHED __builtin_amdgcn_sched_barrier(0)
; template <class Epi>
; __device__ __forceinline__ void gemm_phase(LAS unsigned char* lds, const Gemm g, const Sched& S, const Epi& E) {
;     ...
;             PG8_LDA(At, 1, 1); PG8_STAGE(PG8_SB(1, 0), b3, voffB); PG8_STAGE(PG8_SB(1, 1), b3 + hstepB, voffB); PG8_STAGE(PG8_SA(1, 0), a3, voffA);
;             PG8_WAIT_V(8); PG8_WAIT_L(0); PG8_BAR; PG8_MMA(1, 0, At, B0); PG8_MMA(1, 1, At, B1); PG8_BAR; PG8_SCHED;
;         }
;         if (wr == 0) PG8_BAR;
	s_add_i32 s34, s76, s3
	v_lshl_add_u64 v[206:207], v[206:207], 0, s[22:23]
	s_mov_b32 m0, s34
	ds_read_b128 v[162:165], v212 offset:49152
	ds_read_b128 v[166:169], v212 offset:50176
	ds_read_b128 v[170:173], v212 offset:51200
	ds_read_b128 v[174:177], v212 offset:52224
	ds_read_b128 v[178:181], v212 offset:53248
	ds_read_b128 v[182:185], v212 offset:54272
	ds_read_b128 v[214:217], v212 offset:55296
	ds_read_b128 v[218:221], v212 offset:56320
	global_load_lds_dwordx4 v[206:207], off
	s_add_i32 m0, s34, 0x2000
	s_add_u32 s30, s30, 0xb0080
	v_lshl_add_u64 v[206:207], v[222:223], 0, s[22:23]
	s_addc_u32 s31, s31, 0
	s_add_i32 s34, s77, s3
	global_load_lds_dwordx4 v[206:207], off
	v_lshl_add_u64 v[206:207], s[30:31], 0, v[188:189]
	s_mov_b32 m0, s34
	s_nop 0
	global_load_lds_dwordx4 v[206:207], off
	v_lshl_add_u64 v[206:207], s[30:31], 0, v[192:193]
	s_add_i32 m0, s34, 0x2000
	s_nop 0
	global_load_lds_dwordx4 v[206:207], off
	v_lshl_add_u64 v[206:207], v[224:225], 0, s[22:23]
	s_mov_b32 m0, s43
	s_nop 0
	global_load_lds_dwordx4 v[206:207], off
	v_lshl_add_u64 v[206:207], v[226:227], 0, s[22:23]
	s_mov_b32 m0, s44
	s_nop 0
	global_load_lds_dwordx4 v[206:207], off
	s_waitcnt vmcnt(8)
	s_waitcnt lgkmcnt(0)
	s_barrier
	s_setprio 1
	s_waitcnt lgkmcnt(0)
	v_mfma_f32_16x16x32_bf16 v[62:65], v[106:109], v[162:165], v[62:65]
	v_mfma_f32_16x16x32_bf16 v[58:61], v[130:133], v[162:165], v[58:61]
	v_mfma_f32_16x16x32_bf16 v[46:49], v[106:109], v[170:173], v[46:49]
	v_mfma_f32_16x16x32_bf16 v[42:45], v[130:133], v[170:173], v[42:45]
	v_mfma_f32_16x16x32_bf16 v[30:33], v[106:109], v[178:181], v[30:33]
	v_mfma_f32_16x16x32_bf16 v[26:29], v[130:133], v[178:181], v[26:29]
	v_mfma_f32_16x16x32_bf16 v[14:17], v[106:109], v[214:217], v[14:17]
	v_mfma_f32_16x16x32_bf16 v[10:13], v[130:133], v[214:217], v[10:13]
	v_mfma_f32_16x16x32_bf16 v[62:65], v[114:117], v[166:169], v[62:65]
	v_mfma_f32_16x16x32_bf16 v[58:61], v[142:145], v[166:169], v[58:61]
	v_mfma_f32_16x16x32_bf16 v[46:49], v[114:117], v[174:177], v[46:49]
	v_mfma_f32_16x16x32_bf16 v[42:45], v[142:145], v[174:177], v[42:45]
	v_mfma_f32_16x16x32_bf16 v[30:33], v[114:117], v[182:185], v[30:33]
	v_mfma_f32_16x16x32_bf16 v[26:29], v[142:145], v[182:185], v[26:29]
	v_mfma_f32_16x16x32_bf16 v[14:17], v[114:117], v[218:221], v[14:17]
	v_mfma_f32_16x16x32_bf16 v[10:13], v[142:145], v[218:221], v[10:13]
	s_setprio 0
	s_setprio 1
	v_mfma_f32_16x16x32_bf16 v[54:57], v[146:149], v[162:165], v[54:57]
	v_mfma_f32_16x16x32_bf16 v[50:53], v[154:157], v[162:165], v[50:53]
	v_mfma_f32_16x16x32_bf16 v[38:41], v[146:149], v[170:173], v[38:41]
	v_mfma_f32_16x16x32_bf16 v[34:37], v[154:157], v[170:173], v[34:37]
	v_mfma_f32_16x16x32_bf16 v[22:25], v[146:149], v[178:181], v[22:25]
	v_mfma_f32_16x16x32_bf16 v[18:21], v[154:157], v[178:181], v[18:21]
	v_mfma_f32_16x16x32_bf16 v[6:9], v[146:149], v[214:217], v[6:9]
	v_mfma_f32_16x16x32_bf16 v[2:5], v[154:157], v[214:217], v[2:5]
	v_mfma_f32_16x16x32_bf16 v[54:57], v[150:153], v[166:169], v[54:57]
	v_mfma_f32_16x16x32_bf16 v[50:53], v[158:161], v[166:169], v[50:53]
	v_mfma_f32_16x16x32_bf16 v[38:41], v[150:153], v[174:177], v[38:41]
	v_mfma_f32_16x16x32_bf16 v[34:37], v[158:161], v[174:177], v[34:37]
	v_mfma_f32_16x16x32_bf16 v[22:25], v[150:153], v[182:185], v[22:25]
	v_mfma_f32_16x16x32_bf16 v[18:21], v[158:161], v[182:185], v[18:21]
	v_mfma_f32_16x16x32_bf16 v[6:9], v[150:153], v[218:221], v[6:9]
	v_mfma_f32_16x16x32_bf16 v[2:5], v[158:161], v[218:221], v[2:5]
	s_setprio 0
	s_barrier
	s_add_i32 s75, s75, 2
	s_add_u32 s8, s8, 0x100
	s_addc_u32 s9, s9, 0
	s_add_u32 s73, s73, 0x100
	s_addc_u32 s74, s74, 0
	s_cmp_gt_u32 s75, 41
	s_cbranch_scc0 .LBB0_1800
	s_and_b64 vcc, exec, s[24:25]
	s_cbranch_vccz .LBB0_1803
	s_barrier

; #define PG8_STAGE(bufoff, gbase, voff) do { _Pragma("unroll") for (int _i = 0; _i < 2; ++_i) \
;         __builtin_amdgcn_global_load_lds((const unsigned*)((const char*)(gbase) + (voff)[_i]), (LAS unsigned*)(lds + (bufoff) + ldsw + _i * 8192), 16, 0, 0); } while (0)
; #define PG8_LDA(dst, b, h) do { _Pragma("unroll") for (int m = 0; m < 4; ++m) _Pragma("unroll") for (int k = 0; k < 2; ++k) dst[m][k] = *(const LAS bf16x8*)(lds + PG8_SA(b, h) + aoff + m * 2048 + k * 1024); } while (0)
; #define PG8_MMA(ai, bj, At, Bt) do { __builtin_amdgcn_s_setprio(1); _Pragma("unroll") for (int m = 0; m < 4; ++m) _Pragma("unroll") for (int n = 0; n < 2; ++n) _Pragma("unroll") for (int k = 0; k < 2; ++k) \
;         acc[ai][bj][m][n] = __builtin_amdgcn_mfma_f32_16x16x32_bf16(Bt[n][k], At[m][k], acc[ai][bj][m][n], 0, 0, 0); __builtin_amdgcn_s_setprio(0); } while (0)
; #define PG8_WAIT_V(n) asm volatile("s_waitcnt vmcnt(" #n ")" ::: "memory")
; #define PG8_WAIT_L(n) asm volatile("s_waitcnt lgkmcnt(" #n ")" ::: "memory")
; #define PG8_BAR __builtin_amdgcn_s_barrier()
; #define PG8_SCHED __builtin_amdgcn_sched_barrier(0)
; template <class Epi>
; __device__ __forceinline__ void gemm_phase(LAS unsigned char* lds, const Gemm g, const Sched& S, const Epi& E) {
;     ...
;             PG8_WAIT_V(8); PG8_WAIT_L(0); PG8_BAR; PG8_MMA(0, 0, At, B0); PG8_MMA(0, 1, At, B1); PG8_BAR; PG8_SCHED;
;             PG8_LDA(At, 0, 1); PG8_STAGE(PG8_SB(0, 0), b2, voffB); PG8_STAGE(PG8_SB(0, 1), b2 + hstepB, voffB); PG8_STAGE(PG8_SA(0, 0), a2, voffA);
;             PG8_WAIT_V(8); PG8_WAIT_L(0); PG8_BAR; PG8_MMA(1, 0, At, B0); PG8_MMA(1, 1, At, B1); PG8_BAR; PG8_SCHED;
.Lcz_p10_0:
	s_barrier
	s_setprio 1
	s_waitcnt lgkmcnt(0)
	v_mfma_f32_16x16x32_bf16 v[138:141], v[106:109], v[162:165], 0
	v_mfma_f32_16x16x32_bf16 v[134:137], v[130:133], v[162:165], 0
	v_mfma_f32_16x16x32_bf16 v[118:121], v[106:109], v[170:173], 0
	v_mfma_f32_16x16x32_bf16 v[110:113], v[130:133], v[170:173], 0
	v_mfma_f32_16x16x32_bf16 v[94:97], v[106:109], v[178:181], 0
	v_mfma_f32_16x16x32_bf16 v[90:93], v[130:133], v[178:181], 0
	v_mfma_f32_16x16x32_bf16 v[78:81], v[106:109], v[214:217], 0
	v_mfma_f32_16x16x32_bf16 v[74:77], v[130:133], v[214:217], 0
	v_mfma_f32_16x16x32_bf16 v[138:141], v[114:117], v[166:169], v[138:141]
	v_mfma_f32_16x16x32_bf16 v[134:137], v[142:145], v[166:169], v[134:137]
	v_mfma_f32_16x16x32_bf16 v[118:121], v[114:117], v[174:177], v[118:121]
	v_mfma_f32_16x16x32_bf16 v[110:113], v[142:145], v[174:177], v[110:113]
	v_mfma_f32_16x16x32_bf16 v[94:97], v[114:117], v[182:185], v[94:97]
	v_mfma_f32_16x16x32_bf16 v[90:93], v[142:145], v[182:185], v[90:93]
	v_mfma_f32_16x16x32_bf16 v[78:81], v[114:117], v[218:221], v[78:81]
	v_mfma_f32_16x16x32_bf16 v[74:77], v[142:145], v[218:221], v[74:77]
	s_setprio 0
	s_setprio 1
	v_mfma_f32_16x16x32_bf16 v[126:129], v[146:149], v[162:165], 0
	v_mfma_f32_16x16x32_bf16 v[122:125], v[154:157], v[162:165], 0
	v_mfma_f32_16x16x32_bf16 v[102:105], v[146:149], v[170:173], 0
	v_mfma_f32_16x16x32_bf16 v[98:101], v[154:157], v[170:173], 0
	v_mfma_f32_16x16x32_bf16 v[86:89], v[146:149], v[178:181], 0
	v_mfma_f32_16x16x32_bf16 v[82:85], v[154:157], v[178:181], 0
	v_mfma_f32_16x16x32_bf16 v[70:73], v[146:149], v[214:217], 0
	v_mfma_f32_16x16x32_bf16 v[66:69], v[154:157], v[214:217], 0
	v_mfma_f32_16x16x32_bf16 v[126:129], v[150:153], v[166:169], v[126:129]
	v_mfma_f32_16x16x32_bf16 v[122:125], v[158:161], v[166:169], v[122:125]
	v_mfma_f32_16x16x32_bf16 v[102:105], v[150:153], v[174:177], v[102:105]
	v_mfma_f32_16x16x32_bf16 v[98:101], v[158:161], v[174:177], v[98:101]
	v_mfma_f32_16x16x32_bf16 v[86:89], v[150:153], v[182:185], v[86:89]
	v_mfma_f32_16x16x32_bf16 v[82:85], v[158:161], v[182:185], v[82:85]
	v_mfma_f32_16x16x32_bf16 v[70:73], v[150:153], v[218:221], v[70:73]
	v_mfma_f32_16x16x32_bf16 v[66:69], v[158:161], v[218:221], v[66:69]
	s_branch .Lcz_p10_0_j
.Lcz_p10_1:
	s_barrier
	s_setprio 1
	s_waitcnt lgkmcnt(0)
	v_mfma_f32_16x16x32_bf16 v[62:65], v[106:109], v[162:165], 0
	v_mfma_f32_16x16x32_bf16 v[58:61], v[130:133], v[162:165], 0
	v_mfma_f32_16x16x32_bf16 v[46:49], v[106:109], v[170:173], 0
	v_mfma_f32_16x16x32_bf16 v[42:45], v[130:133], v[170:173], 0
	v_mfma_f32_16x16x32_bf16 v[30:33], v[106:109], v[178:181], 0
	v_mfma_f32_16x16x32_bf16 v[26:29], v[130:133], v[178:181], 0
	v_mfma_f32_16x16x32_bf16 v[14:17], v[106:109], v[214:217], 0
	v_mfma_f32_16x16x32_bf16 v[10:13], v[130:133], v[214:217], 0
	v_mfma_f32_16x16x32_bf16 v[62:65], v[114:117], v[166:169], v[62:65]
	v_mfma_f32_16x16x32_bf16 v[58:61], v[142:145], v[166:169], v[58:61]
	v_mfma_f32_16x16x32_bf16 v[46:49], v[114:117], v[174:177], v[46:49]
	v_mfma_f32_16x16x32_bf16 v[42:45], v[142:145], v[174:177], v[42:45]
	v_mfma_f32_16x16x32_bf16 v[30:33], v[114:117], v[182:185], v[30:33]
	v_mfma_f32_16x16x32_bf16 v[26:29], v[142:145], v[182:185], v[26:29]
	v_mfma_f32_16x16x32_bf16 v[14:17], v[114:117], v[218:221], v[14:17]
	v_mfma_f32_16x16x32_bf16 v[10:13], v[142:145], v[218:221], v[10:13]
	s_setprio 0
	s_setprio 1
	v_mfma_f32_16x16x32_bf16 v[54:57], v[146:149], v[162:165], 0
	v_mfma_f32_16x16x32_bf16 v[50:53], v[154:157], v[162:165], 0
	v_mfma_f32_16x16x32_bf16 v[38:41], v[146:149], v[170:173], 0
	v_mfma_f32_16x16x32_bf16 v[34:37], v[154:157], v[170:173], 0
	v_mfma_f32_16x16x32_bf16 v[22:25], v[146:149], v[178:181], 0
	v_mfma_f32_16x16x32_bf16 v[18:21], v[154:157], v[178:181], 0
	v_mfma_f32_16x16x32_bf16 v[6:9], v[146:149], v[214:217], 0
	v_mfma_f32_16x16x32_bf16 v[2:5], v[154:157], v[214:217], 0
	v_mfma_f32_16x16x32_bf16 v[54:57], v[150:153], v[166:169], v[54:57]
	v_mfma_f32_16x16x32_bf16 v[50:53], v[158:161], v[166:169], v[50:53]
	v_mfma_f32_16x16x32_bf16 v[38:41], v[150:153], v[174:177], v[38:41]
	v_mfma_f32_16x16x32_bf16 v[34:37], v[158:161], v[174:177], v[34:37]
	v_mfma_f32_16x16x32_bf16 v[22:25], v[150:153], v[182:185], v[22:25]
	v_mfma_f32_16x16x32_bf16 v[18:21], v[158:161], v[182:185], v[18:21]
	v_mfma_f32_16x16x32_bf16 v[6:9], v[150:153], v[218:221], v[6:9]
	v_mfma_f32_16x16x32_bf16 v[2:5], v[158:161], v[218:221], v[2:5]
	s_branch .Lcz_p10_1_j
